# attention/retention PV sections: counted lgkmcnt waits per V-fragment consumer instead of lgkmcnt(0) after each fragment read batch
# speedup vs baseline: 1.0061x; 1.0061x over previous
; template <int D0> __device__ __forceinline__ void pv_one(f32x16& od, int vb, bf16x8 pa0, bf16x8 pa1, bf16x8 pa2, bf16x8 pa3) {
;   const s16x4 l0 = tr_read<v_rd_off(D0, 0, 0)>(vb), h0 = tr_read<v_rd_off(D0, 0, 1)>(vb), l1 = tr_read<v_rd_off(D0, 1, 0)>(vb), h1 = tr_read<v_rd_off(D0, 1, 1)>(vb);
;   const s16x4 l2 = tr_read<v_rd_off(D0, 2, 0)>(vb), h2 = tr_read<v_rd_off(D0, 2, 1)>(vb), l3 = tr_read<v_rd_off(D0, 3, 0)>(vb), h3 = tr_read<v_rd_off(D0, 3, 1)>(vb);
;   asm volatile("s_waitcnt lgkmcnt(0)" ::: "memory"); SBAR();
;     ...
;   od = __builtin_amdgcn_mfma_f32_32x32x16_bf16(pa0, PK(l0, h0), od, 0, 0, 0);
;   od = __builtin_amdgcn_mfma_f32_32x32x16_bf16(pa1, PK(l1, h1), od, 0, 0, 0);
;   od = __builtin_amdgcn_mfma_f32_32x32x16_bf16(pa2, PK(l2, h2), od, 0, 0, 0);
;   od = __builtin_amdgcn_mfma_f32_32x32x16_bf16(pa3, PK(l3, h3), od, 0, 0, 0);
;     ...
; }
; __device__ __forceinline__ void pv_d0(f32x16* o, int vb, bf16x8 pa0, bf16x8 pa1, bf16x8 pa2, bf16x8 pa3) {
;   pv_one<0>(o[0], vb, pa0, pa1, pa2, pa3); pv_one<1>(o[1], vb, pa0, pa1, pa2, pa3); pv_one<2>(o[2], vb, pa0, pa1, pa2, pa3); pv_one<3>(o[3], vb, pa0, pa1, pa2, pa3);
; }
; __device__ __forceinline__ void pack_p(const f32x16& p0, const f32x16& p1, bf16x8& pa0, bf16x8& pa1, bf16x8& pa2, bf16x8& pa3) {
;     ...
;   PK4(p0, 0, pa0); PK4(p0, 8, pa1); PK4(p1, 0, pa2); PK4(p1, 8, pa3);
;     ...
; }
; template <int DQK>
; __device__ __forceinline__ void partialSM(f32x16& p0, f32x16& p1, float& m_reg, float& mn, float& alpha) {
;   constexpr float SCALE = DQK == 128 ? 0.088388347648318440f : 0.072168783648703220f;
;   constexpr float C = SCALE * LOG2E;
;   float pmax = p0[0];
; #pragma unroll
;   for (int r = 1; r < 16; ++r) pmax = fmaxf(pmax, p0[r]);
; #pragma unroll
;   for (int r = 0; r < 16; ++r) pmax = fmaxf(pmax, p1[r]);
;   { auto rr = __builtin_amdgcn_permlane32_swap(__float_as_uint(pmax), __float_as_uint(pmax), false, false);
;     pmax = fmaxf(__uint_as_float(rr[0]), __uint_as_float(rr[1])); }
;   if (__builtin_expect(__all(pmax - m_reg <= THR / SCALE), 1)) { mn = m_reg; alpha = 1.f; }
;   else { mn = fmaxf(m_reg, pmax); alpha = __builtin_amdgcn_exp2f((m_reg - mn) * C); m_reg = mn; }
;   const float mnC = -mn * C;
; #pragma unroll
;   for (int r = 0; r < 16; ++r) p0[r] = fmaf(p0[r], C, mnC);
; #pragma unroll
;   for (int r = 0; r < 16; ++r) p1[r] = fmaf(p1[r], C, mnC);
; #pragma unroll
.LBB0_833:
	v_cndmask_b32_e64 v205, v207, v205, s[6:7]
	s_barrier
	v_mul_f32_e32 v207, 0xbdd53b94, v205
	v_fmamk_f32 v82, v82, 0x3dd53b94, v207
	v_fmamk_f32 v83, v83, 0x3dd53b94, v207
	v_fmamk_f32 v84, v84, 0x3dd53b94, v207
	v_fmamk_f32 v85, v85, 0x3dd53b94, v207
	v_fmamk_f32 v86, v86, 0x3dd53b94, v207
	v_fmamk_f32 v87, v87, 0x3dd53b94, v207
	v_fmamk_f32 v88, v88, 0x3dd53b94, v207
	v_fmamk_f32 v89, v89, 0x3dd53b94, v207
	v_fmamk_f32 v90, v90, 0x3dd53b94, v207
	v_fmamk_f32 v91, v91, 0x3dd53b94, v207
	v_fmamk_f32 v92, v92, 0x3dd53b94, v207
	v_fmamk_f32 v93, v93, 0x3dd53b94, v207
	v_fmamk_f32 v94, v94, 0x3dd53b94, v207
	v_fmamk_f32 v95, v95, 0x3dd53b94, v207
	v_fmamk_f32 v96, v96, 0x3dd53b94, v207
	v_fmamk_f32 v97, v97, 0x3dd53b94, v207
	v_fmamk_f32 v66, v66, 0x3dd53b94, v207
	v_fmamk_f32 v67, v67, 0x3dd53b94, v207
	v_fmamk_f32 v68, v68, 0x3dd53b94, v207
	v_fmamk_f32 v69, v69, 0x3dd53b94, v207
	v_fmamk_f32 v70, v70, 0x3dd53b94, v207
	v_fmamk_f32 v71, v71, 0x3dd53b94, v207
	v_fmamk_f32 v72, v72, 0x3dd53b94, v207
	v_fmamk_f32 v73, v73, 0x3dd53b94, v207
	v_fmamk_f32 v74, v74, 0x3dd53b94, v207
	v_fmamk_f32 v75, v75, 0x3dd53b94, v207
	v_fmamk_f32 v76, v76, 0x3dd53b94, v207
	v_fmamk_f32 v77, v77, 0x3dd53b94, v207
	v_fmamk_f32 v78, v78, 0x3dd53b94, v207
	v_fmamk_f32 v79, v79, 0x3dd53b94, v207
	v_fmamk_f32 v80, v80, 0x3dd53b94, v207
	v_fmac_f32_e32 v207, 0x3dd53b94, v81
	v_exp_f32_e32 v81, v82
	v_exp_f32_e32 v82, v83
	v_exp_f32_e32 v83, v84
	v_exp_f32_e32 v84, v85
	v_exp_f32_e32 v85, v86
	v_exp_f32_e32 v86, v87
	v_exp_f32_e32 v87, v88
	v_exp_f32_e32 v88, v89
	v_exp_f32_e32 v89, v90
	v_exp_f32_e32 v90, v91
	v_exp_f32_e32 v91, v92
	v_exp_f32_e32 v92, v93
	v_exp_f32_e32 v93, v94
	v_exp_f32_e32 v94, v95
	v_exp_f32_e32 v95, v96
	v_exp_f32_e32 v96, v97
	v_exp_f32_e32 v97, v66
	v_add_f32_e32 v66, 0, v81
	v_add_f32_e32 v66, v82, v66
	v_add_f32_e32 v66, v83, v66
	v_add_f32_e32 v66, v84, v66
	v_add_f32_e32 v66, v85, v66
	v_add_f32_e32 v66, v86, v66
	v_add_f32_e32 v66, v87, v66
	v_add_f32_e32 v66, v88, v66
	v_add_f32_e32 v66, v89, v66
	v_add_f32_e32 v66, v90, v66
	v_add_f32_e32 v66, v91, v66
	v_add_f32_e32 v66, v92, v66
	v_add_f32_e32 v66, v93, v66
	v_exp_f32_e32 v208, v67
	v_add_f32_e32 v66, v94, v66
	v_exp_f32_e32 v209, v68
	v_add_f32_e32 v66, v95, v66
	v_exp_f32_e32 v210, v69
	v_add_f32_e32 v66, v96, v66
	v_exp_f32_e32 v211, v70
	v_add_f32_e32 v66, v97, v66
	v_exp_f32_e32 v212, v71
	v_add_f32_e32 v66, v208, v66
	v_exp_f32_e32 v213, v72
	v_add_f32_e32 v66, v209, v66
	v_exp_f32_e32 v214, v73
	v_add_f32_e32 v66, v210, v66
	v_exp_f32_e32 v215, v74
	v_add_f32_e32 v66, v211, v66
	v_exp_f32_e32 v216, v75
	v_add_f32_e32 v66, v212, v66
	v_exp_f32_e32 v217, v76
	v_add_f32_e32 v66, v213, v66
	v_exp_f32_e32 v218, v77
	v_add_f32_e32 v66, v214, v66
	v_exp_f32_e32 v219, v78
	v_add_f32_e32 v66, v215, v66
	v_exp_f32_e32 v220, v79
	v_add_f32_e32 v66, v216, v66
	v_exp_f32_e32 v221, v80
	v_add_f32_e32 v66, v217, v66
	v_exp_f32_e32 v207, v207
	v_add_f32_e32 v66, v218, v66
	v_add_f32_e32 v66, v219, v66
	v_add_f32_e32 v66, v220, v66
	v_add_f32_e32 v66, v221, v66
	v_add_f32_e32 v66, v207, v66
	v_mov_b32_e32 v67, v66
	s_nop 1
	v_permlane32_swap_b32_e32 v66, v67
	v_cvt_pk_bf16_f32 v68, v81, v82
	v_cvt_pk_bf16_f32 v69, v83, v84
	v_cvt_pk_bf16_f32 v70, v85, v86
	v_cvt_pk_bf16_f32 v71, v87, v88
	v_cvt_pk_bf16_f32 v72, v89, v90
	v_cvt_pk_bf16_f32 v73, v91, v92
	v_cvt_pk_bf16_f32 v74, v93, v94
	v_cvt_pk_bf16_f32 v75, v95, v96
	v_cvt_pk_bf16_f32 v76, v97, v208
	v_cvt_pk_bf16_f32 v77, v209, v210
	v_cvt_pk_bf16_f32 v78, v211, v212
	v_cvt_pk_bf16_f32 v79, v213, v214
	v_cvt_pk_bf16_f32 v80, v215, v216
	v_cvt_pk_bf16_f32 v81, v217, v218
	v_cvt_pk_bf16_f32 v82, v219, v220
	v_cvt_pk_bf16_f32 v83, v221, v207
	v_permlane32_swap_b32_e32 v68, v70
	v_permlane32_swap_b32_e32 v69, v71
	v_permlane32_swap_b32_e32 v72, v74
	v_permlane32_swap_b32_e32 v73, v75
	v_permlane32_swap_b32_e32 v76, v78
	v_permlane32_swap_b32_e32 v77, v79
	v_permlane32_swap_b32_e32 v80, v82
	v_permlane32_swap_b32_e32 v81, v83
	v_lshl_add_u32 v96, s42, 14, v204
	s_setprio 1
	ds_read_b64_tr_b16 v[84:85], v96 offset:0
	ds_read_b64_tr_b16 v[86:87], v96 offset:0x800
	ds_read_b64_tr_b16 v[88:89], v96 offset:0x1000
	ds_read_b64_tr_b16 v[90:91], v96 offset:0x1800
	ds_read_b64_tr_b16 v[92:93], v96 offset:0x2000
	ds_read_b64_tr_b16 v[94:95], v96 offset:0x2800
	ds_read_b64_tr_b16 v[208:209], v96 offset:0x3000
	ds_read_b64_tr_b16 v[210:211], v96 offset:0x3800
	s_waitcnt lgkmcnt(0)
	s_nop 0
	v_mfma_f32_32x32x16_bf16 v[2:17], v[68:71], v[84:87], v[2:17]
	ds_read_b64_tr_b16 v[84:85], v96 offset:0x200
	ds_read_b64_tr_b16 v[86:87], v96 offset:0xa00
	v_mfma_f32_32x32x16_bf16 v[2:17], v[72:75], v[88:91], v[2:17]
	ds_read_b64_tr_b16 v[88:89], v96 offset:0x1200
	ds_read_b64_tr_b16 v[90:91], v96 offset:0x1a00
	v_mfma_f32_32x32x16_bf16 v[2:17], v[76:79], v[92:95], v[2:17]
	ds_read_b64_tr_b16 v[92:93], v96 offset:0x2200
	ds_read_b64_tr_b16 v[94:95], v96 offset:0x2a00
	ds_read_b64_tr_b16 v[212:213], v96 offset:0x3200
	ds_read_b64_tr_b16 v[214:215], v96 offset:0x3a00
	v_mfma_f32_32x32x16_bf16 v[2:17], v[80:83], v[208:211], v[2:17]
	s_waitcnt lgkmcnt(6)
	v_mfma_f32_32x32x16_bf16 v[50:65], v[68:71], v[84:87], v[50:65]
	ds_read_b64_tr_b16 v[84:85], v96 offset:0x400
	ds_read_b64_tr_b16 v[86:87], v96 offset:0xc00
	s_waitcnt lgkmcnt(6)
	v_mfma_f32_32x32x16_bf16 v[50:65], v[72:75], v[88:91], v[50:65]
	ds_read_b64_tr_b16 v[88:89], v96 offset:0x1400
	ds_read_b64_tr_b16 v[90:91], v96 offset:0x1c00
	s_waitcnt lgkmcnt(6)
	v_mfma_f32_32x32x16_bf16 v[50:65], v[76:79], v[92:95], v[50:65]
	ds_read_b64_tr_b16 v[92:93], v96 offset:0x2400
	ds_read_b64_tr_b16 v[94:95], v96 offset:0x2c00
	ds_read_b64_tr_b16 v[208:209], v96 offset:0x3400
	ds_read_b64_tr_b16 v[210:211], v96 offset:0x3c00
	s_waitcnt lgkmcnt(8)
	v_mfma_f32_32x32x16_bf16 v[50:65], v[80:83], v[212:215], v[50:65]
	s_waitcnt lgkmcnt(6)
	v_mfma_f32_32x32x16_bf16 v[34:49], v[68:71], v[84:87], v[34:49]
	ds_read_b64_tr_b16 v[84:85], v96 offset:0x600
	ds_read_b64_tr_b16 v[86:87], v96 offset:0xe00
	s_waitcnt lgkmcnt(6)
	v_mfma_f32_32x32x16_bf16 v[34:49], v[72:75], v[88:91], v[34:49]
	ds_read_b64_tr_b16 v[88:89], v96 offset:0x1600
	ds_read_b64_tr_b16 v[90:91], v96 offset:0x1e00
	s_waitcnt lgkmcnt(6)
	v_mfma_f32_32x32x16_bf16 v[34:49], v[76:79], v[92:95], v[34:49]
	ds_read_b64_tr_b16 v[92:93], v96 offset:0x2600
	ds_read_b64_tr_b16 v[94:95], v96 offset:0x2e00
	ds_read_b64_tr_b16 v[212:213], v96 offset:0x3600
	ds_read_b64_tr_b16 v[214:215], v96 offset:0x3e00
	s_waitcnt lgkmcnt(8)
	v_mfma_f32_32x32x16_bf16 v[34:49], v[80:83], v[208:211], v[34:49]
	s_waitcnt lgkmcnt(6)
	v_mfma_f32_32x32x16_bf16 v[18:33], v[68:71], v[84:87], v[18:33]
	s_andn2_b64 vcc, exec, s[18:19]
	s_waitcnt lgkmcnt(4)
	v_mfma_f32_32x32x16_bf16 v[18:33], v[72:75], v[88:91], v[18:33]
	s_waitcnt lgkmcnt(2)
	v_mfma_f32_32x32x16_bf16 v[18:33], v[76:79], v[92:95], v[18:33]
	s_waitcnt lgkmcnt(0)
	v_mfma_f32_32x32x16_bf16 v[18:33], v[80:83], v[212:215], v[18:33]
	s_setprio 0
	s_cbranch_vccnz .LBB0_835
; #define SWRITE(b, i) do { *(bf16x8*)(V_lds + (b) * SH::V + vst0) = sr_[i].vs0; *(bf16x8*)(V_lds + (b) * SH::V + vst1) = sr_[i].vs1; \
;     _Pragma("unroll") for (int q_ = 0; q_ < KPT; ++q_) *(bf16x8*)(K_lds + (b) * SH::K + KSWZ(krow[q_], kcol[q_] * 2)) = sr_[i].ks[q_]; } while (0)
; template <int DQK, int MODE, int SDEPTH, int ldq, int ldk, int ldv, int ldo, int ldg> ...
;     ...
;       if (j + 1 < NT) { asm volatile("s_waitcnt vmcnt(0)" ::: "memory"); SWRITE(bsel ^ 1, 0); }
	s_xor_b32 s6, s42, 1
	s_lshl_b32 s7, s6, 14
	s_add_i32 s7, s7, 0
	v_add_u32_e32 v68, s7, v183
	s_lshl_b32 s6, s6, 13
	s_waitcnt vmcnt(0)
	ds_write_b128 v68, v[98:101]
	v_add_u32_e32 v68, s7, v182
	s_add_i32 s7, s7, s6
	ds_write_b128 v68, v[102:105]
	v_add3_u32 v68, s7, v184, v185
	ds_write_b128 v68, v[106:109] offset:32768
	v_add3_u32 v68, s7, v186, v187
	ds_write_b128 v68, v[110:113] offset:32768
	v_add3_u32 v68, s7, v188, v189
	ds_write_b128 v68, v[134:137] offset:32768

; template <int D0> __device__ __forceinline__ void pv_one(f32x16& od, int vb, bf16x8 pa0, bf16x8 pa1, bf16x8 pa2, bf16x8 pa3) {
;   const s16x4 l0 = tr_read<v_rd_off(D0, 0, 0)>(vb), h0 = tr_read<v_rd_off(D0, 0, 1)>(vb), l1 = tr_read<v_rd_off(D0, 1, 0)>(vb), h1 = tr_read<v_rd_off(D0, 1, 1)>(vb);
;   const s16x4 l2 = tr_read<v_rd_off(D0, 2, 0)>(vb), h2 = tr_read<v_rd_off(D0, 2, 1)>(vb), l3 = tr_read<v_rd_off(D0, 3, 0)>(vb), h3 = tr_read<v_rd_off(D0, 3, 1)>(vb);
;   asm volatile("s_waitcnt lgkmcnt(0)" ::: "memory"); SBAR();
;     ...
;   od = __builtin_amdgcn_mfma_f32_32x32x16_bf16(pa0, PK(l0, h0), od, 0, 0, 0);
;   od = __builtin_amdgcn_mfma_f32_32x32x16_bf16(pa1, PK(l1, h1), od, 0, 0, 0);
;   od = __builtin_amdgcn_mfma_f32_32x32x16_bf16(pa2, PK(l2, h2), od, 0, 0, 0);
;   od = __builtin_amdgcn_mfma_f32_32x32x16_bf16(pa3, PK(l3, h3), od, 0, 0, 0);
;     ...
; }
; __device__ __forceinline__ void pv_d0(f32x16* o, int vb, bf16x8 pa0, bf16x8 pa1, bf16x8 pa2, bf16x8 pa3) {
;   pv_one<0>(o[0], vb, pa0, pa1, pa2, pa3); pv_one<1>(o[1], vb, pa0, pa1, pa2, pa3); pv_one<2>(o[2], vb, pa0, pa1, pa2, pa3); pv_one<3>(o[3], vb, pa0, pa1, pa2, pa3);
; }
; __device__ __forceinline__ void pack_p(const f32x16& p0, const f32x16& p1, bf16x8& pa0, bf16x8& pa1, bf16x8& pa2, bf16x8& pa3) {
;     ...
;   PK4(p0, 0, pa0); PK4(p0, 8, pa1); PK4(p1, 0, pa2); PK4(p1, 8, pa3);
;     ...
; }
; template <int DQK>
; __device__ __forceinline__ void partialSM(f32x16& p0, f32x16& p1, float& m_reg, float& mn, float& alpha) {
;   constexpr float SCALE = DQK == 128 ? 0.088388347648318440f : 0.072168783648703220f;
;   constexpr float C = SCALE * LOG2E;
;   float pmax = p0[0];
; #pragma unroll
;   for (int r = 1; r < 16; ++r) pmax = fmaxf(pmax, p0[r]);
; #pragma unroll
;   for (int r = 0; r < 16; ++r) pmax = fmaxf(pmax, p1[r]);
;   { auto rr = __builtin_amdgcn_permlane32_swap(__float_as_uint(pmax), __float_as_uint(pmax), false, false);
;     pmax = fmaxf(__uint_as_float(rr[0]), __uint_as_float(rr[1])); }
;   if (__builtin_expect(__all(pmax - m_reg <= THR / SCALE), 1)) { mn = m_reg; alpha = 1.f; }
;   else { mn = fmaxf(m_reg, pmax); alpha = __builtin_amdgcn_exp2f((m_reg - mn) * C); m_reg = mn; }
;   const float mnC = -mn * C;
; #pragma unroll
;   for (int r = 0; r < 16; ++r) p0[r] = fmaf(p0[r], C, mnC);
; #pragma unroll
;   for (int r = 0; r < 16; ++r) p1[r] = fmaf(p1[r], C, mnC);
; #pragma unroll
.Lm1_BY_nl:
	v_mul_f32_e32 v207, 0xbdd53b94, v205
	v_fmamk_f32 v82, v82, 0x3dd53b94, v207
	v_fmamk_f32 v83, v83, 0x3dd53b94, v207
	v_fmamk_f32 v84, v84, 0x3dd53b94, v207
	v_fmamk_f32 v85, v85, 0x3dd53b94, v207
	v_fmamk_f32 v86, v86, 0x3dd53b94, v207
	v_fmamk_f32 v87, v87, 0x3dd53b94, v207
	v_fmamk_f32 v88, v88, 0x3dd53b94, v207
	v_fmamk_f32 v89, v89, 0x3dd53b94, v207
	v_fmamk_f32 v90, v90, 0x3dd53b94, v207
	v_fmamk_f32 v91, v91, 0x3dd53b94, v207
	v_fmamk_f32 v92, v92, 0x3dd53b94, v207
	v_fmamk_f32 v93, v93, 0x3dd53b94, v207
	v_fmamk_f32 v94, v94, 0x3dd53b94, v207
	v_fmamk_f32 v95, v95, 0x3dd53b94, v207
	v_fmamk_f32 v96, v96, 0x3dd53b94, v207
	v_fmamk_f32 v97, v97, 0x3dd53b94, v207
	v_fmamk_f32 v66, v66, 0x3dd53b94, v207
	v_fmamk_f32 v67, v67, 0x3dd53b94, v207
	v_fmamk_f32 v68, v68, 0x3dd53b94, v207
	v_fmamk_f32 v69, v69, 0x3dd53b94, v207
	v_fmamk_f32 v70, v70, 0x3dd53b94, v207
	v_fmamk_f32 v71, v71, 0x3dd53b94, v207
	v_fmamk_f32 v72, v72, 0x3dd53b94, v207
	v_fmamk_f32 v73, v73, 0x3dd53b94, v207
	v_fmamk_f32 v74, v74, 0x3dd53b94, v207
	v_fmamk_f32 v75, v75, 0x3dd53b94, v207
	v_fmamk_f32 v76, v76, 0x3dd53b94, v207
	v_fmamk_f32 v77, v77, 0x3dd53b94, v207
	v_fmamk_f32 v78, v78, 0x3dd53b94, v207
	v_fmamk_f32 v79, v79, 0x3dd53b94, v207
	v_fmamk_f32 v80, v80, 0x3dd53b94, v207
	v_fmac_f32_e32 v207, 0x3dd53b94, v81
	v_exp_f32_e32 v81, v82
	v_exp_f32_e32 v82, v83
	v_exp_f32_e32 v83, v84
	v_exp_f32_e32 v84, v85
	v_exp_f32_e32 v85, v86
	v_exp_f32_e32 v86, v87
	v_exp_f32_e32 v87, v88
	v_exp_f32_e32 v88, v89
	v_exp_f32_e32 v89, v90
	v_exp_f32_e32 v90, v91
	v_exp_f32_e32 v91, v92
	v_exp_f32_e32 v92, v93
	v_exp_f32_e32 v93, v94
	v_exp_f32_e32 v94, v95
	v_exp_f32_e32 v95, v96
	v_exp_f32_e32 v96, v97
	v_exp_f32_e32 v97, v66
	v_add_f32_e32 v66, 0, v81
	v_add_f32_e32 v66, v82, v66
	v_add_f32_e32 v66, v83, v66
	v_add_f32_e32 v66, v84, v66
	v_add_f32_e32 v66, v85, v66
	v_add_f32_e32 v66, v86, v66
	v_add_f32_e32 v66, v87, v66
	v_add_f32_e32 v66, v88, v66
	v_add_f32_e32 v66, v89, v66
	v_add_f32_e32 v66, v90, v66
	v_add_f32_e32 v66, v91, v66
	v_add_f32_e32 v66, v92, v66
	v_add_f32_e32 v66, v93, v66
	v_exp_f32_e32 v208, v67
	v_add_f32_e32 v66, v94, v66
	v_exp_f32_e32 v209, v68
	v_add_f32_e32 v66, v95, v66
	v_exp_f32_e32 v210, v69
	v_add_f32_e32 v66, v96, v66
	v_exp_f32_e32 v211, v70
	v_add_f32_e32 v66, v97, v66
	v_exp_f32_e32 v212, v71
	v_add_f32_e32 v66, v208, v66
	v_exp_f32_e32 v213, v72
	v_add_f32_e32 v66, v209, v66
	v_exp_f32_e32 v214, v73
	v_add_f32_e32 v66, v210, v66
	v_exp_f32_e32 v215, v74
	v_add_f32_e32 v66, v211, v66
	v_exp_f32_e32 v216, v75
	v_add_f32_e32 v66, v212, v66
	v_exp_f32_e32 v217, v76
	v_add_f32_e32 v66, v213, v66
	v_exp_f32_e32 v218, v77
	v_add_f32_e32 v66, v214, v66
	v_exp_f32_e32 v219, v78
	v_add_f32_e32 v66, v215, v66
	v_exp_f32_e32 v220, v79
	v_add_f32_e32 v66, v216, v66
	v_exp_f32_e32 v221, v80
	v_add_f32_e32 v66, v217, v66
	v_exp_f32_e32 v207, v207
	v_add_f32_e32 v66, v218, v66
	v_add_f32_e32 v66, v219, v66
	v_add_f32_e32 v66, v220, v66
	v_add_f32_e32 v66, v221, v66
	v_add_f32_e32 v66, v207, v66
	v_mov_b32_e32 v67, v66
	s_nop 1
	v_permlane32_swap_b32_e32 v66, v67
	v_cvt_pk_bf16_f32 v68, v81, v82
	v_cvt_pk_bf16_f32 v69, v83, v84
	v_cvt_pk_bf16_f32 v70, v85, v86
	v_cvt_pk_bf16_f32 v71, v87, v88
	v_cvt_pk_bf16_f32 v72, v89, v90
	v_cvt_pk_bf16_f32 v73, v91, v92
	v_cvt_pk_bf16_f32 v74, v93, v94
	v_cvt_pk_bf16_f32 v75, v95, v96
	v_cvt_pk_bf16_f32 v76, v97, v208
	v_cvt_pk_bf16_f32 v77, v209, v210
	v_cvt_pk_bf16_f32 v78, v211, v212
	v_cvt_pk_bf16_f32 v79, v213, v214
	v_cvt_pk_bf16_f32 v80, v215, v216
	v_cvt_pk_bf16_f32 v81, v217, v218
	v_cvt_pk_bf16_f32 v82, v219, v220
	v_cvt_pk_bf16_f32 v83, v221, v207
	v_permlane32_swap_b32_e32 v68, v70
	v_permlane32_swap_b32_e32 v69, v71
	v_permlane32_swap_b32_e32 v72, v74
	v_permlane32_swap_b32_e32 v73, v75
	v_permlane32_swap_b32_e32 v76, v78
	v_permlane32_swap_b32_e32 v77, v79
	v_permlane32_swap_b32_e32 v80, v82
	v_permlane32_swap_b32_e32 v81, v83
	v_lshl_add_u32 v96, s42, 14, v204
	s_setprio 1
	ds_read_b64_tr_b16 v[84:85], v96 offset:0
	ds_read_b64_tr_b16 v[86:87], v96 offset:0x800
	ds_read_b64_tr_b16 v[88:89], v96 offset:0x1000
	ds_read_b64_tr_b16 v[90:91], v96 offset:0x1800
	ds_read_b64_tr_b16 v[92:93], v96 offset:0x2000
	ds_read_b64_tr_b16 v[94:95], v96 offset:0x2800
	ds_read_b64_tr_b16 v[208:209], v96 offset:0x3000
	ds_read_b64_tr_b16 v[210:211], v96 offset:0x3800
	s_waitcnt lgkmcnt(0)
	s_nop 0
	v_mfma_f32_32x32x16_bf16 v[2:17], v[68:71], v[84:87], v[2:17]
	ds_read_b64_tr_b16 v[84:85], v96 offset:0x200
	ds_read_b64_tr_b16 v[86:87], v96 offset:0xa00
	v_mfma_f32_32x32x16_bf16 v[2:17], v[72:75], v[88:91], v[2:17]
	ds_read_b64_tr_b16 v[88:89], v96 offset:0x1200
	ds_read_b64_tr_b16 v[90:91], v96 offset:0x1a00
	v_mfma_f32_32x32x16_bf16 v[2:17], v[76:79], v[92:95], v[2:17]
	ds_read_b64_tr_b16 v[92:93], v96 offset:0x2200
	ds_read_b64_tr_b16 v[94:95], v96 offset:0x2a00
	ds_read_b64_tr_b16 v[212:213], v96 offset:0x3200
	ds_read_b64_tr_b16 v[214:215], v96 offset:0x3a00
	v_mfma_f32_32x32x16_bf16 v[2:17], v[80:83], v[208:211], v[2:17]
	s_waitcnt lgkmcnt(6)
	v_mfma_f32_32x32x16_bf16 v[50:65], v[68:71], v[84:87], v[50:65]
	ds_read_b64_tr_b16 v[84:85], v96 offset:0x400
	ds_read_b64_tr_b16 v[86:87], v96 offset:0xc00
	s_waitcnt lgkmcnt(6)
	v_mfma_f32_32x32x16_bf16 v[50:65], v[72:75], v[88:91], v[50:65]
	ds_read_b64_tr_b16 v[88:89], v96 offset:0x1400
	ds_read_b64_tr_b16 v[90:91], v96 offset:0x1c00
	s_waitcnt lgkmcnt(6)
	v_mfma_f32_32x32x16_bf16 v[50:65], v[76:79], v[92:95], v[50:65]
	ds_read_b64_tr_b16 v[92:93], v96 offset:0x2400
	ds_read_b64_tr_b16 v[94:95], v96 offset:0x2c00
	ds_read_b64_tr_b16 v[208:209], v96 offset:0x3400
	ds_read_b64_tr_b16 v[210:211], v96 offset:0x3c00
	s_waitcnt lgkmcnt(8)
	v_mfma_f32_32x32x16_bf16 v[50:65], v[80:83], v[212:215], v[50:65]
	s_waitcnt lgkmcnt(6)
	v_mfma_f32_32x32x16_bf16 v[34:49], v[68:71], v[84:87], v[34:49]
	ds_read_b64_tr_b16 v[84:85], v96 offset:0x600
	ds_read_b64_tr_b16 v[86:87], v96 offset:0xe00
	s_waitcnt lgkmcnt(6)
	v_mfma_f32_32x32x16_bf16 v[34:49], v[72:75], v[88:91], v[34:49]
	ds_read_b64_tr_b16 v[88:89], v96 offset:0x1600
	ds_read_b64_tr_b16 v[90:91], v96 offset:0x1e00
	s_waitcnt lgkmcnt(6)
	v_mfma_f32_32x32x16_bf16 v[34:49], v[76:79], v[92:95], v[34:49]
	ds_read_b64_tr_b16 v[92:93], v96 offset:0x2600
	ds_read_b64_tr_b16 v[94:95], v96 offset:0x2e00
	ds_read_b64_tr_b16 v[212:213], v96 offset:0x3600
	ds_read_b64_tr_b16 v[214:215], v96 offset:0x3e00
	s_waitcnt lgkmcnt(8)
	v_mfma_f32_32x32x16_bf16 v[34:49], v[80:83], v[208:211], v[34:49]
	s_waitcnt lgkmcnt(6)
	v_mfma_f32_32x32x16_bf16 v[18:33], v[68:71], v[84:87], v[18:33]
	s_waitcnt lgkmcnt(4)
	v_mfma_f32_32x32x16_bf16 v[18:33], v[72:75], v[88:91], v[18:33]
	s_waitcnt lgkmcnt(2)
	v_mfma_f32_32x32x16_bf16 v[18:33], v[76:79], v[92:95], v[18:33]
	s_waitcnt lgkmcnt(0)
	v_mfma_f32_32x32x16_bf16 v[18:33], v[80:83], v[212:215], v[18:33]
	s_setprio 0
	v_add_f32_e32 v66, v66, v67
	v_fmac_f32_e32 v66, v169, v206
	s_waitcnt lgkmcnt(0)
	v_mov_b32_e32 v169, v66
	s_barrier
; #define SBAR() __builtin_amdgcn_sched_barrier(0)
; #define SLOAD(i, k0) do { sr_[i].vs0 = *reinterpret_cast<const bf16x8*>(&Vh[(long)((k0) + sr) * ldv + sc]); sr_[i].vs1 = *reinterpret_cast<const bf16x8*>(&Vh[(long)((k0) + 32 + sr) * ldv + sc]); \
;     _Pragma("unroll") for (int q_ = 0; q_ < KPT; ++q_) sr_[i].ks[q_] = *reinterpret_cast<const bf16x8*>(&Kh[(long)((k0) + krow[q_]) * ldk + kcol[q_]]); } while (0)
; #define SWRITE(b, i) do { *(bf16x8*)(V_lds + (b) * SH::V + vst0) = sr_[i].vs0; *(bf16x8*)(V_lds + (b) * SH::V + vst1) = sr_[i].vs1; \
;     _Pragma("unroll") for (int q_ = 0; q_ < KPT; ++q_) *(bf16x8*)(K_lds + (b) * SH::K + KSWZ(krow[q_], kcol[q_] * 2)) = sr_[i].ks[q_]; } while (0)
; #define RESC(a) do { if (__any((a) < 1.f)) { if (hi == 0) al_l[r32] = (a); asm volatile("s_waitcnt lgkmcnt(0)" ::: "memory"); \
;     _Pragma("unroll") for (int d = 0; d < 4; ++d) _Pragma("unroll") for (int r = 0; r < 16; ++r) o[d][r] *= al_l[crow(r, hi)]; } } while (0)
; #define PART(P0, P1, tj, MN, AL) do { if constexpr (MODE == 0) partialSM<DQK>(P0, P1, m_reg, MN, AL); else ret_weights(P0, P1, TKIND(tj), nlane - (float)(64 * (tj) - 256), lf2, lb2); } while (0)
; #define FIN(P0, P1, AL) do { if constexpr (MODE == 0) finishSM(P0, P1, AL, l_reg, pa0, pa1, pa2, pa3); else pack_p(P0, P1, pa0, pa1, pa2, pa3); } while (0)
; template <int DQK, int MODE, int SDEPTH, int ldq, int ldk, int ldv, int ldo, int ldg> ...
;     ...
;     for (int j = 0; j < NT; ++j) {
;       const int bsel = j & 1;
;       if (j + 1 < NT) SLOAD(0, (j + 1) * KVBLK);
;       SBAR(); QKT(pA0, pA1, K_lds + bsel * SH::K);
;       PART(pA0, pA1, j, mnA, alA);
;       if constexpr (MODE == 0) RESC(alA);
;       FIN(pA0, pA1, alA); SBAR();
;       pv_d0(o, vb0 + bsel * SH::V, pa0, pa1, pa2, pa3);
;       if (j + 1 < NT) { asm volatile("s_waitcnt vmcnt(0)" ::: "memory"); SWRITE(bsel ^ 1, 0); }
;       __syncthreads();
;     }
	s_cmp_eq_u32 s41, 36
	s_cbranch_scc1 .LBB0_837

; template <int D0> __device__ __forceinline__ void pv_one(f32x16& od, int vb, bf16x8 pa0, bf16x8 pa1, bf16x8 pa2, bf16x8 pa3) {
;   const s16x4 l0 = tr_read<v_rd_off(D0, 0, 0)>(vb), h0 = tr_read<v_rd_off(D0, 0, 1)>(vb), l1 = tr_read<v_rd_off(D0, 1, 0)>(vb), h1 = tr_read<v_rd_off(D0, 1, 1)>(vb);
;   const s16x4 l2 = tr_read<v_rd_off(D0, 2, 0)>(vb), h2 = tr_read<v_rd_off(D0, 2, 1)>(vb), l3 = tr_read<v_rd_off(D0, 3, 0)>(vb), h3 = tr_read<v_rd_off(D0, 3, 1)>(vb);
;   asm volatile("s_waitcnt lgkmcnt(0)" ::: "memory"); SBAR();
;     ...
;   od = __builtin_amdgcn_mfma_f32_32x32x16_bf16(pa0, PK(l0, h0), od, 0, 0, 0);
;   od = __builtin_amdgcn_mfma_f32_32x32x16_bf16(pa1, PK(l1, h1), od, 0, 0, 0);
;   od = __builtin_amdgcn_mfma_f32_32x32x16_bf16(pa2, PK(l2, h2), od, 0, 0, 0);
;   od = __builtin_amdgcn_mfma_f32_32x32x16_bf16(pa3, PK(l3, h3), od, 0, 0, 0);
;     ...
; }
; __device__ __forceinline__ void pv_d0(f32x16* o, int vb, bf16x8 pa0, bf16x8 pa1, bf16x8 pa2, bf16x8 pa3) {
;   pv_one<0>(o[0], vb, pa0, pa1, pa2, pa3); pv_one<1>(o[1], vb, pa0, pa1, pa2, pa3); pv_one<2>(o[2], vb, pa0, pa1, pa2, pa3); pv_one<3>(o[3], vb, pa0, pa1, pa2, pa3);
; }
; __device__ __forceinline__ void pack_p(const f32x16& p0, const f32x16& p1, bf16x8& pa0, bf16x8& pa1, bf16x8& pa2, bf16x8& pa3) {
;     ...
;   PK4(p0, 0, pa0); PK4(p0, 8, pa1); PK4(p1, 0, pa2); PK4(p1, 8, pa3);
;     ...
; }
; template <int DQK>
; __device__ __forceinline__ void partialSM(f32x16& p0, f32x16& p1, float& m_reg, float& mn, float& alpha) {
;   constexpr float SCALE = DQK == 128 ? 0.088388347648318440f : 0.072168783648703220f;
;   constexpr float C = SCALE * LOG2E;
;   float pmax = p0[0];
; #pragma unroll
;   for (int r = 1; r < 16; ++r) pmax = fmaxf(pmax, p0[r]);
; #pragma unroll
;   for (int r = 0; r < 16; ++r) pmax = fmaxf(pmax, p1[r]);
;   { auto rr = __builtin_amdgcn_permlane32_swap(__float_as_uint(pmax), __float_as_uint(pmax), false, false);
;     pmax = fmaxf(__uint_as_float(rr[0]), __uint_as_float(rr[1])); }
;   if (__builtin_expect(__all(pmax - m_reg <= THR / SCALE), 1)) { mn = m_reg; alpha = 1.f; }
;   else { mn = fmaxf(m_reg, pmax); alpha = __builtin_amdgcn_exp2f((m_reg - mn) * C); m_reg = mn; }
;   const float mnC = -mn * C;
; #pragma unroll
;   for (int r = 0; r < 16; ++r) p0[r] = fmaf(p0[r], C, mnC);
; #pragma unroll
;   for (int r = 0; r < 16; ++r) p1[r] = fmaf(p1[r], C, mnC);
; #pragma unroll
.LBB0_900:
	v_cndmask_b32_e64 v205, v207, v205, s[6:7]
	s_barrier
	v_mul_f32_e32 v207, 0xbdd53b94, v205
	v_fmamk_f32 v82, v82, 0x3dd53b94, v207
	v_fmamk_f32 v83, v83, 0x3dd53b94, v207
	v_fmamk_f32 v84, v84, 0x3dd53b94, v207
	v_fmamk_f32 v85, v85, 0x3dd53b94, v207
	v_fmamk_f32 v86, v86, 0x3dd53b94, v207
	v_fmamk_f32 v87, v87, 0x3dd53b94, v207
	v_fmamk_f32 v88, v88, 0x3dd53b94, v207
	v_fmamk_f32 v89, v89, 0x3dd53b94, v207
	v_fmamk_f32 v90, v90, 0x3dd53b94, v207
	v_fmamk_f32 v91, v91, 0x3dd53b94, v207
	v_fmamk_f32 v92, v92, 0x3dd53b94, v207
	v_fmamk_f32 v93, v93, 0x3dd53b94, v207
	v_fmamk_f32 v94, v94, 0x3dd53b94, v207
	v_fmamk_f32 v95, v95, 0x3dd53b94, v207
	v_fmamk_f32 v96, v96, 0x3dd53b94, v207
	v_fmamk_f32 v97, v97, 0x3dd53b94, v207
	v_fmamk_f32 v66, v66, 0x3dd53b94, v207
	v_fmamk_f32 v67, v67, 0x3dd53b94, v207
	v_fmamk_f32 v68, v68, 0x3dd53b94, v207
	v_fmamk_f32 v69, v69, 0x3dd53b94, v207
	v_fmamk_f32 v70, v70, 0x3dd53b94, v207
	v_fmamk_f32 v71, v71, 0x3dd53b94, v207
	v_fmamk_f32 v72, v72, 0x3dd53b94, v207
	v_fmamk_f32 v73, v73, 0x3dd53b94, v207
	v_fmamk_f32 v74, v74, 0x3dd53b94, v207
	v_fmamk_f32 v75, v75, 0x3dd53b94, v207
	v_fmamk_f32 v76, v76, 0x3dd53b94, v207
	v_fmamk_f32 v77, v77, 0x3dd53b94, v207
	v_fmamk_f32 v78, v78, 0x3dd53b94, v207
	v_fmamk_f32 v79, v79, 0x3dd53b94, v207
	v_fmamk_f32 v80, v80, 0x3dd53b94, v207
	v_fmac_f32_e32 v207, 0x3dd53b94, v81
	v_exp_f32_e32 v81, v82
	v_exp_f32_e32 v82, v83
	v_exp_f32_e32 v83, v84
	v_exp_f32_e32 v84, v85
	v_exp_f32_e32 v85, v86
	v_exp_f32_e32 v86, v87
	v_exp_f32_e32 v87, v88
	v_exp_f32_e32 v88, v89
	v_exp_f32_e32 v89, v90
	v_exp_f32_e32 v90, v91
	v_exp_f32_e32 v91, v92
	v_exp_f32_e32 v92, v93
	v_exp_f32_e32 v93, v94
	v_exp_f32_e32 v94, v95
	v_exp_f32_e32 v95, v96
	v_exp_f32_e32 v96, v97
	v_exp_f32_e32 v97, v66
	v_add_f32_e32 v66, 0, v81
	v_add_f32_e32 v66, v82, v66
	v_add_f32_e32 v66, v83, v66
	v_add_f32_e32 v66, v84, v66
	v_add_f32_e32 v66, v85, v66
	v_add_f32_e32 v66, v86, v66
	v_add_f32_e32 v66, v87, v66
	v_add_f32_e32 v66, v88, v66
	v_add_f32_e32 v66, v89, v66
	v_add_f32_e32 v66, v90, v66
	v_add_f32_e32 v66, v91, v66
	v_add_f32_e32 v66, v92, v66
	v_add_f32_e32 v66, v93, v66
	v_exp_f32_e32 v208, v67
	v_add_f32_e32 v66, v94, v66
	v_exp_f32_e32 v209, v68
	v_add_f32_e32 v66, v95, v66
	v_exp_f32_e32 v210, v69
	v_add_f32_e32 v66, v96, v66
	v_exp_f32_e32 v211, v70
	v_add_f32_e32 v66, v97, v66
	v_exp_f32_e32 v212, v71
	v_add_f32_e32 v66, v208, v66
	v_exp_f32_e32 v213, v72
	v_add_f32_e32 v66, v209, v66
	v_exp_f32_e32 v214, v73
	v_add_f32_e32 v66, v210, v66
	v_exp_f32_e32 v215, v74
	v_add_f32_e32 v66, v211, v66
	v_exp_f32_e32 v216, v75
	v_add_f32_e32 v66, v212, v66
	v_exp_f32_e32 v217, v76
	v_add_f32_e32 v66, v213, v66
	v_exp_f32_e32 v218, v77
	v_add_f32_e32 v66, v214, v66
	v_exp_f32_e32 v219, v78
	v_add_f32_e32 v66, v215, v66
	v_exp_f32_e32 v220, v79
	v_add_f32_e32 v66, v216, v66
	v_exp_f32_e32 v221, v80
	v_add_f32_e32 v66, v217, v66
	v_exp_f32_e32 v207, v207
	v_add_f32_e32 v66, v218, v66
	v_add_f32_e32 v66, v219, v66
	v_add_f32_e32 v66, v220, v66
	v_add_f32_e32 v66, v221, v66
	v_add_f32_e32 v66, v207, v66
	v_mov_b32_e32 v67, v66
	s_nop 1
	v_permlane32_swap_b32_e32 v66, v67
	v_cvt_pk_bf16_f32 v68, v81, v82
	v_cvt_pk_bf16_f32 v69, v83, v84
	v_cvt_pk_bf16_f32 v70, v85, v86
	v_cvt_pk_bf16_f32 v71, v87, v88
	v_cvt_pk_bf16_f32 v72, v89, v90
	v_cvt_pk_bf16_f32 v73, v91, v92
	v_cvt_pk_bf16_f32 v74, v93, v94
	v_cvt_pk_bf16_f32 v75, v95, v96
	v_cvt_pk_bf16_f32 v76, v97, v208
	v_cvt_pk_bf16_f32 v77, v209, v210
	v_cvt_pk_bf16_f32 v78, v211, v212
	v_cvt_pk_bf16_f32 v79, v213, v214
	v_cvt_pk_bf16_f32 v80, v215, v216
	v_cvt_pk_bf16_f32 v81, v217, v218
	v_cvt_pk_bf16_f32 v82, v219, v220
	v_cvt_pk_bf16_f32 v83, v221, v207
	v_permlane32_swap_b32_e32 v68, v70
	v_permlane32_swap_b32_e32 v69, v71
	v_permlane32_swap_b32_e32 v72, v74
	v_permlane32_swap_b32_e32 v73, v75
	v_permlane32_swap_b32_e32 v76, v78
	v_permlane32_swap_b32_e32 v77, v79
	v_permlane32_swap_b32_e32 v80, v82
	v_permlane32_swap_b32_e32 v81, v83
	v_lshl_add_u32 v96, s38, 14, v204
	s_setprio 1
	ds_read_b64_tr_b16 v[84:85], v96 offset:0
	ds_read_b64_tr_b16 v[86:87], v96 offset:0x800
	ds_read_b64_tr_b16 v[88:89], v96 offset:0x1000
	ds_read_b64_tr_b16 v[90:91], v96 offset:0x1800
	ds_read_b64_tr_b16 v[92:93], v96 offset:0x2000
	ds_read_b64_tr_b16 v[94:95], v96 offset:0x2800
	ds_read_b64_tr_b16 v[208:209], v96 offset:0x3000
	ds_read_b64_tr_b16 v[210:211], v96 offset:0x3800
	s_waitcnt lgkmcnt(0)
	s_nop 0
	v_mfma_f32_32x32x16_bf16 v[2:17], v[68:71], v[84:87], v[2:17]
	ds_read_b64_tr_b16 v[84:85], v96 offset:0x200
	ds_read_b64_tr_b16 v[86:87], v96 offset:0xa00
	v_mfma_f32_32x32x16_bf16 v[2:17], v[72:75], v[88:91], v[2:17]
	ds_read_b64_tr_b16 v[88:89], v96 offset:0x1200
	ds_read_b64_tr_b16 v[90:91], v96 offset:0x1a00
	v_mfma_f32_32x32x16_bf16 v[2:17], v[76:79], v[92:95], v[2:17]
	ds_read_b64_tr_b16 v[92:93], v96 offset:0x2200
	ds_read_b64_tr_b16 v[94:95], v96 offset:0x2a00
	ds_read_b64_tr_b16 v[212:213], v96 offset:0x3200
	ds_read_b64_tr_b16 v[214:215], v96 offset:0x3a00
	v_mfma_f32_32x32x16_bf16 v[2:17], v[80:83], v[208:211], v[2:17]
	s_waitcnt lgkmcnt(6)
	v_mfma_f32_32x32x16_bf16 v[50:65], v[68:71], v[84:87], v[50:65]
	ds_read_b64_tr_b16 v[84:85], v96 offset:0x400
	ds_read_b64_tr_b16 v[86:87], v96 offset:0xc00
	s_waitcnt lgkmcnt(6)
	v_mfma_f32_32x32x16_bf16 v[50:65], v[72:75], v[88:91], v[50:65]
	ds_read_b64_tr_b16 v[88:89], v96 offset:0x1400
	ds_read_b64_tr_b16 v[90:91], v96 offset:0x1c00
	s_waitcnt lgkmcnt(6)
	v_mfma_f32_32x32x16_bf16 v[50:65], v[76:79], v[92:95], v[50:65]
	ds_read_b64_tr_b16 v[92:93], v96 offset:0x2400
	ds_read_b64_tr_b16 v[94:95], v96 offset:0x2c00
	ds_read_b64_tr_b16 v[208:209], v96 offset:0x3400
	ds_read_b64_tr_b16 v[210:211], v96 offset:0x3c00
	s_waitcnt lgkmcnt(8)
	v_mfma_f32_32x32x16_bf16 v[50:65], v[80:83], v[212:215], v[50:65]
	s_waitcnt lgkmcnt(6)
	v_mfma_f32_32x32x16_bf16 v[34:49], v[68:71], v[84:87], v[34:49]
	ds_read_b64_tr_b16 v[84:85], v96 offset:0x600
	ds_read_b64_tr_b16 v[86:87], v96 offset:0xe00
	s_waitcnt lgkmcnt(6)
	v_mfma_f32_32x32x16_bf16 v[34:49], v[72:75], v[88:91], v[34:49]
	ds_read_b64_tr_b16 v[88:89], v96 offset:0x1600
	ds_read_b64_tr_b16 v[90:91], v96 offset:0x1e00
	s_waitcnt lgkmcnt(6)
	v_mfma_f32_32x32x16_bf16 v[34:49], v[76:79], v[92:95], v[34:49]
	ds_read_b64_tr_b16 v[92:93], v96 offset:0x2600
	ds_read_b64_tr_b16 v[94:95], v96 offset:0x2e00
	ds_read_b64_tr_b16 v[212:213], v96 offset:0x3600
	ds_read_b64_tr_b16 v[214:215], v96 offset:0x3e00
	s_waitcnt lgkmcnt(8)
	v_mfma_f32_32x32x16_bf16 v[34:49], v[80:83], v[208:211], v[34:49]
	s_waitcnt lgkmcnt(6)
	v_mfma_f32_32x32x16_bf16 v[18:33], v[68:71], v[84:87], v[18:33]
	s_andn2_b64 vcc, exec, s[18:19]
	s_waitcnt lgkmcnt(4)
	v_mfma_f32_32x32x16_bf16 v[18:33], v[72:75], v[88:91], v[18:33]
	s_waitcnt lgkmcnt(2)
	v_mfma_f32_32x32x16_bf16 v[18:33], v[76:79], v[92:95], v[18:33]
	s_waitcnt lgkmcnt(0)
	v_mfma_f32_32x32x16_bf16 v[18:33], v[80:83], v[212:215], v[18:33]
	s_setprio 0
	s_cbranch_vccnz .LBB0_902
; #define SWRITE(b, i) do { *(bf16x8*)(V_lds + (b) * SH::V + vst0) = sr_[i].vs0; *(bf16x8*)(V_lds + (b) * SH::V + vst1) = sr_[i].vs1; \
;     _Pragma("unroll") for (int q_ = 0; q_ < KPT; ++q_) *(bf16x8*)(K_lds + (b) * SH::K + KSWZ(krow[q_], kcol[q_] * 2)) = sr_[i].ks[q_]; } while (0)
; template <int DQK, int MODE, int SDEPTH, int ldq, int ldk, int ldv, int ldo, int ldg> ...
;     ...
;       if (j + 1 < NT) { asm volatile("s_waitcnt vmcnt(0)" ::: "memory"); SWRITE(bsel ^ 1, 0); }
	s_xor_b32 s6, s38, 1
	s_lshl_b32 s7, s6, 14
	s_add_i32 s7, s7, 0
	v_add_u32_e32 v68, s7, v183
	s_lshl_b32 s6, s6, 13
	s_waitcnt vmcnt(0)
	ds_write_b128 v68, v[98:101]
	v_add_u32_e32 v68, s7, v182
	s_add_i32 s7, s7, s6
	ds_write_b128 v68, v[102:105]
	v_add3_u32 v68, s7, v184, v185
	ds_write_b128 v68, v[106:109] offset:32768
	v_add3_u32 v68, s7, v186, v187
	ds_write_b128 v68, v[110:113] offset:32768
	v_add3_u32 v68, s7, v188, v189
	ds_write_b128 v68, v[142:145] offset:32768

; template <int D0> __device__ __forceinline__ void pv_one(f32x16& od, int vb, bf16x8 pa0, bf16x8 pa1, bf16x8 pa2, bf16x8 pa3) {
;   const s16x4 l0 = tr_read<v_rd_off(D0, 0, 0)>(vb), h0 = tr_read<v_rd_off(D0, 0, 1)>(vb), l1 = tr_read<v_rd_off(D0, 1, 0)>(vb), h1 = tr_read<v_rd_off(D0, 1, 1)>(vb);
;   const s16x4 l2 = tr_read<v_rd_off(D0, 2, 0)>(vb), h2 = tr_read<v_rd_off(D0, 2, 1)>(vb), l3 = tr_read<v_rd_off(D0, 3, 0)>(vb), h3 = tr_read<v_rd_off(D0, 3, 1)>(vb);
;   asm volatile("s_waitcnt lgkmcnt(0)" ::: "memory"); SBAR();
;     ...
;   od = __builtin_amdgcn_mfma_f32_32x32x16_bf16(pa0, PK(l0, h0), od, 0, 0, 0);
;   od = __builtin_amdgcn_mfma_f32_32x32x16_bf16(pa1, PK(l1, h1), od, 0, 0, 0);
;   od = __builtin_amdgcn_mfma_f32_32x32x16_bf16(pa2, PK(l2, h2), od, 0, 0, 0);
;   od = __builtin_amdgcn_mfma_f32_32x32x16_bf16(pa3, PK(l3, h3), od, 0, 0, 0);
;     ...
; }
; __device__ __forceinline__ void pv_d0(f32x16* o, int vb, bf16x8 pa0, bf16x8 pa1, bf16x8 pa2, bf16x8 pa3) {
;   pv_one<0>(o[0], vb, pa0, pa1, pa2, pa3); pv_one<1>(o[1], vb, pa0, pa1, pa2, pa3); pv_one<2>(o[2], vb, pa0, pa1, pa2, pa3); pv_one<3>(o[3], vb, pa0, pa1, pa2, pa3);
; }
; __device__ __forceinline__ void pack_p(const f32x16& p0, const f32x16& p1, bf16x8& pa0, bf16x8& pa1, bf16x8& pa2, bf16x8& pa3) {
;     ...
;   PK4(p0, 0, pa0); PK4(p0, 8, pa1); PK4(p1, 0, pa2); PK4(p1, 8, pa3);
;     ...
; }
; template <int DQK>
; __device__ __forceinline__ void partialSM(f32x16& p0, f32x16& p1, float& m_reg, float& mn, float& alpha) {
;   constexpr float SCALE = DQK == 128 ? 0.088388347648318440f : 0.072168783648703220f;
;   constexpr float C = SCALE * LOG2E;
;   float pmax = p0[0];
; #pragma unroll
;   for (int r = 1; r < 16; ++r) pmax = fmaxf(pmax, p0[r]);
; #pragma unroll
;   for (int r = 0; r < 16; ++r) pmax = fmaxf(pmax, p1[r]);
;   { auto rr = __builtin_amdgcn_permlane32_swap(__float_as_uint(pmax), __float_as_uint(pmax), false, false);
;     pmax = fmaxf(__uint_as_float(rr[0]), __uint_as_float(rr[1])); }
;   if (__builtin_expect(__all(pmax - m_reg <= THR / SCALE), 1)) { mn = m_reg; alpha = 1.f; }
;   else { mn = fmaxf(m_reg, pmax); alpha = __builtin_amdgcn_exp2f((m_reg - mn) * C); m_reg = mn; }
;   const float mnC = -mn * C;
; #pragma unroll
;   for (int r = 0; r < 16; ++r) p0[r] = fmaf(p0[r], C, mnC);
; #pragma unroll
;   for (int r = 0; r < 16; ++r) p1[r] = fmaf(p1[r], C, mnC);
; #pragma unroll
.Lm2_BY_nl:
	v_mul_f32_e32 v207, 0xbdd53b94, v205
	v_fmamk_f32 v82, v82, 0x3dd53b94, v207
	v_fmamk_f32 v83, v83, 0x3dd53b94, v207
	v_fmamk_f32 v84, v84, 0x3dd53b94, v207
	v_fmamk_f32 v85, v85, 0x3dd53b94, v207
	v_fmamk_f32 v86, v86, 0x3dd53b94, v207
	v_fmamk_f32 v87, v87, 0x3dd53b94, v207
	v_fmamk_f32 v88, v88, 0x3dd53b94, v207
	v_fmamk_f32 v89, v89, 0x3dd53b94, v207
	v_fmamk_f32 v90, v90, 0x3dd53b94, v207
	v_fmamk_f32 v91, v91, 0x3dd53b94, v207
	v_fmamk_f32 v92, v92, 0x3dd53b94, v207
	v_fmamk_f32 v93, v93, 0x3dd53b94, v207
	v_fmamk_f32 v94, v94, 0x3dd53b94, v207
	v_fmamk_f32 v95, v95, 0x3dd53b94, v207
	v_fmamk_f32 v96, v96, 0x3dd53b94, v207
	v_fmamk_f32 v97, v97, 0x3dd53b94, v207
	v_fmamk_f32 v66, v66, 0x3dd53b94, v207
	v_fmamk_f32 v67, v67, 0x3dd53b94, v207
	v_fmamk_f32 v68, v68, 0x3dd53b94, v207
	v_fmamk_f32 v69, v69, 0x3dd53b94, v207
	v_fmamk_f32 v70, v70, 0x3dd53b94, v207
	v_fmamk_f32 v71, v71, 0x3dd53b94, v207
	v_fmamk_f32 v72, v72, 0x3dd53b94, v207
	v_fmamk_f32 v73, v73, 0x3dd53b94, v207
	v_fmamk_f32 v74, v74, 0x3dd53b94, v207
	v_fmamk_f32 v75, v75, 0x3dd53b94, v207
	v_fmamk_f32 v76, v76, 0x3dd53b94, v207
	v_fmamk_f32 v77, v77, 0x3dd53b94, v207
	v_fmamk_f32 v78, v78, 0x3dd53b94, v207
	v_fmamk_f32 v79, v79, 0x3dd53b94, v207
	v_fmamk_f32 v80, v80, 0x3dd53b94, v207
	v_fmac_f32_e32 v207, 0x3dd53b94, v81
	v_exp_f32_e32 v81, v82
	v_exp_f32_e32 v82, v83
	v_exp_f32_e32 v83, v84
	v_exp_f32_e32 v84, v85
	v_exp_f32_e32 v85, v86
	v_exp_f32_e32 v86, v87
	v_exp_f32_e32 v87, v88
	v_exp_f32_e32 v88, v89
	v_exp_f32_e32 v89, v90
	v_exp_f32_e32 v90, v91
	v_exp_f32_e32 v91, v92
	v_exp_f32_e32 v92, v93
	v_exp_f32_e32 v93, v94
	v_exp_f32_e32 v94, v95
	v_exp_f32_e32 v95, v96
	v_exp_f32_e32 v96, v97
	v_exp_f32_e32 v97, v66
	v_add_f32_e32 v66, 0, v81
	v_add_f32_e32 v66, v82, v66
	v_add_f32_e32 v66, v83, v66
	v_add_f32_e32 v66, v84, v66
	v_add_f32_e32 v66, v85, v66
	v_add_f32_e32 v66, v86, v66
	v_add_f32_e32 v66, v87, v66
	v_add_f32_e32 v66, v88, v66
	v_add_f32_e32 v66, v89, v66
	v_add_f32_e32 v66, v90, v66
	v_add_f32_e32 v66, v91, v66
	v_add_f32_e32 v66, v92, v66
	v_add_f32_e32 v66, v93, v66
	v_exp_f32_e32 v208, v67
	v_add_f32_e32 v66, v94, v66
	v_exp_f32_e32 v209, v68
	v_add_f32_e32 v66, v95, v66
	v_exp_f32_e32 v210, v69
	v_add_f32_e32 v66, v96, v66
	v_exp_f32_e32 v211, v70
	v_add_f32_e32 v66, v97, v66
	v_exp_f32_e32 v212, v71
	v_add_f32_e32 v66, v208, v66
	v_exp_f32_e32 v213, v72
	v_add_f32_e32 v66, v209, v66
	v_exp_f32_e32 v214, v73
	v_add_f32_e32 v66, v210, v66
	v_exp_f32_e32 v215, v74
	v_add_f32_e32 v66, v211, v66
	v_exp_f32_e32 v216, v75
	v_add_f32_e32 v66, v212, v66
	v_exp_f32_e32 v217, v76
	v_add_f32_e32 v66, v213, v66
	v_exp_f32_e32 v218, v77
	v_add_f32_e32 v66, v214, v66
	v_exp_f32_e32 v219, v78
	v_add_f32_e32 v66, v215, v66
	v_exp_f32_e32 v220, v79
	v_add_f32_e32 v66, v216, v66
	v_exp_f32_e32 v221, v80
	v_add_f32_e32 v66, v217, v66
	v_exp_f32_e32 v207, v207
	v_add_f32_e32 v66, v218, v66
	v_add_f32_e32 v66, v219, v66
	v_add_f32_e32 v66, v220, v66
	v_add_f32_e32 v66, v221, v66
	v_add_f32_e32 v66, v207, v66
	v_mov_b32_e32 v67, v66
	s_nop 1
	v_permlane32_swap_b32_e32 v66, v67
	v_cvt_pk_bf16_f32 v68, v81, v82
	v_cvt_pk_bf16_f32 v69, v83, v84
	v_cvt_pk_bf16_f32 v70, v85, v86
	v_cvt_pk_bf16_f32 v71, v87, v88
	v_cvt_pk_bf16_f32 v72, v89, v90
	v_cvt_pk_bf16_f32 v73, v91, v92
	v_cvt_pk_bf16_f32 v74, v93, v94
	v_cvt_pk_bf16_f32 v75, v95, v96
	v_cvt_pk_bf16_f32 v76, v97, v208
	v_cvt_pk_bf16_f32 v77, v209, v210
	v_cvt_pk_bf16_f32 v78, v211, v212
	v_cvt_pk_bf16_f32 v79, v213, v214
	v_cvt_pk_bf16_f32 v80, v215, v216
	v_cvt_pk_bf16_f32 v81, v217, v218
	v_cvt_pk_bf16_f32 v82, v219, v220
	v_cvt_pk_bf16_f32 v83, v221, v207
	v_permlane32_swap_b32_e32 v68, v70
	v_permlane32_swap_b32_e32 v69, v71
	v_permlane32_swap_b32_e32 v72, v74
	v_permlane32_swap_b32_e32 v73, v75
	v_permlane32_swap_b32_e32 v76, v78
	v_permlane32_swap_b32_e32 v77, v79
	v_permlane32_swap_b32_e32 v80, v82
	v_permlane32_swap_b32_e32 v81, v83
	v_lshl_add_u32 v96, s38, 14, v204
	s_setprio 1
	ds_read_b64_tr_b16 v[84:85], v96 offset:0
	ds_read_b64_tr_b16 v[86:87], v96 offset:0x800
	ds_read_b64_tr_b16 v[88:89], v96 offset:0x1000
	ds_read_b64_tr_b16 v[90:91], v96 offset:0x1800
	ds_read_b64_tr_b16 v[92:93], v96 offset:0x2000
	ds_read_b64_tr_b16 v[94:95], v96 offset:0x2800
	ds_read_b64_tr_b16 v[208:209], v96 offset:0x3000
	ds_read_b64_tr_b16 v[210:211], v96 offset:0x3800
	s_waitcnt lgkmcnt(0)
	s_nop 0
	v_mfma_f32_32x32x16_bf16 v[2:17], v[68:71], v[84:87], v[2:17]
	ds_read_b64_tr_b16 v[84:85], v96 offset:0x200
	ds_read_b64_tr_b16 v[86:87], v96 offset:0xa00
	v_mfma_f32_32x32x16_bf16 v[2:17], v[72:75], v[88:91], v[2:17]
	ds_read_b64_tr_b16 v[88:89], v96 offset:0x1200
	ds_read_b64_tr_b16 v[90:91], v96 offset:0x1a00
	v_mfma_f32_32x32x16_bf16 v[2:17], v[76:79], v[92:95], v[2:17]
	ds_read_b64_tr_b16 v[92:93], v96 offset:0x2200
	ds_read_b64_tr_b16 v[94:95], v96 offset:0x2a00
	ds_read_b64_tr_b16 v[212:213], v96 offset:0x3200
	ds_read_b64_tr_b16 v[214:215], v96 offset:0x3a00
	v_mfma_f32_32x32x16_bf16 v[2:17], v[80:83], v[208:211], v[2:17]
	s_waitcnt lgkmcnt(6)
	v_mfma_f32_32x32x16_bf16 v[50:65], v[68:71], v[84:87], v[50:65]
	ds_read_b64_tr_b16 v[84:85], v96 offset:0x400
	ds_read_b64_tr_b16 v[86:87], v96 offset:0xc00
	s_waitcnt lgkmcnt(6)
	v_mfma_f32_32x32x16_bf16 v[50:65], v[72:75], v[88:91], v[50:65]
	ds_read_b64_tr_b16 v[88:89], v96 offset:0x1400
	ds_read_b64_tr_b16 v[90:91], v96 offset:0x1c00
	s_waitcnt lgkmcnt(6)
	v_mfma_f32_32x32x16_bf16 v[50:65], v[76:79], v[92:95], v[50:65]
	ds_read_b64_tr_b16 v[92:93], v96 offset:0x2400
	ds_read_b64_tr_b16 v[94:95], v96 offset:0x2c00
	ds_read_b64_tr_b16 v[208:209], v96 offset:0x3400
	ds_read_b64_tr_b16 v[210:211], v96 offset:0x3c00
	s_waitcnt lgkmcnt(8)
	v_mfma_f32_32x32x16_bf16 v[50:65], v[80:83], v[212:215], v[50:65]
	s_waitcnt lgkmcnt(6)
	v_mfma_f32_32x32x16_bf16 v[34:49], v[68:71], v[84:87], v[34:49]
	ds_read_b64_tr_b16 v[84:85], v96 offset:0x600
	ds_read_b64_tr_b16 v[86:87], v96 offset:0xe00
	s_waitcnt lgkmcnt(6)
	v_mfma_f32_32x32x16_bf16 v[34:49], v[72:75], v[88:91], v[34:49]
	ds_read_b64_tr_b16 v[88:89], v96 offset:0x1600
	ds_read_b64_tr_b16 v[90:91], v96 offset:0x1e00
	s_waitcnt lgkmcnt(6)
	v_mfma_f32_32x32x16_bf16 v[34:49], v[76:79], v[92:95], v[34:49]
	ds_read_b64_tr_b16 v[92:93], v96 offset:0x2600
	ds_read_b64_tr_b16 v[94:95], v96 offset:0x2e00
	ds_read_b64_tr_b16 v[212:213], v96 offset:0x3600
	ds_read_b64_tr_b16 v[214:215], v96 offset:0x3e00
	s_waitcnt lgkmcnt(8)
	v_mfma_f32_32x32x16_bf16 v[34:49], v[80:83], v[208:211], v[34:49]
	s_waitcnt lgkmcnt(6)
	v_mfma_f32_32x32x16_bf16 v[18:33], v[68:71], v[84:87], v[18:33]
	s_waitcnt lgkmcnt(4)
	v_mfma_f32_32x32x16_bf16 v[18:33], v[72:75], v[88:91], v[18:33]
	s_waitcnt lgkmcnt(2)
	v_mfma_f32_32x32x16_bf16 v[18:33], v[76:79], v[92:95], v[18:33]
	s_waitcnt lgkmcnt(0)
	v_mfma_f32_32x32x16_bf16 v[18:33], v[80:83], v[212:215], v[18:33]
	s_setprio 0
	v_add_f32_e32 v66, v66, v67
	v_fmac_f32_e32 v66, v169, v206
	s_waitcnt lgkmcnt(0)
	v_mov_b32_e32 v169, v66
	s_barrier
; #define SBAR() __builtin_amdgcn_sched_barrier(0)
; #define SLOAD(i, k0) do { sr_[i].vs0 = *reinterpret_cast<const bf16x8*>(&Vh[(long)((k0) + sr) * ldv + sc]); sr_[i].vs1 = *reinterpret_cast<const bf16x8*>(&Vh[(long)((k0) + 32 + sr) * ldv + sc]); \
;     _Pragma("unroll") for (int q_ = 0; q_ < KPT; ++q_) sr_[i].ks[q_] = *reinterpret_cast<const bf16x8*>(&Kh[(long)((k0) + krow[q_]) * ldk + kcol[q_]]); } while (0)
; #define SWRITE(b, i) do { *(bf16x8*)(V_lds + (b) * SH::V + vst0) = sr_[i].vs0; *(bf16x8*)(V_lds + (b) * SH::V + vst1) = sr_[i].vs1; \
;     _Pragma("unroll") for (int q_ = 0; q_ < KPT; ++q_) *(bf16x8*)(K_lds + (b) * SH::K + KSWZ(krow[q_], kcol[q_] * 2)) = sr_[i].ks[q_]; } while (0)
; #define RESC(a) do { if (__any((a) < 1.f)) { if (hi == 0) al_l[r32] = (a); asm volatile("s_waitcnt lgkmcnt(0)" ::: "memory"); \
;     _Pragma("unroll") for (int d = 0; d < 4; ++d) _Pragma("unroll") for (int r = 0; r < 16; ++r) o[d][r] *= al_l[crow(r, hi)]; } } while (0)
; #define PART(P0, P1, tj, MN, AL) do { if constexpr (MODE == 0) partialSM<DQK>(P0, P1, m_reg, MN, AL); else ret_weights(P0, P1, TKIND(tj), nlane - (float)(64 * (tj) - 256), lf2, lb2); } while (0)
; #define FIN(P0, P1, AL) do { if constexpr (MODE == 0) finishSM(P0, P1, AL, l_reg, pa0, pa1, pa2, pa3); else pack_p(P0, P1, pa0, pa1, pa2, pa3); } while (0)
; template <int DQK, int MODE, int SDEPTH, int ldq, int ldk, int ldv, int ldo, int ldg> ...
;     ...
;     for (int j = 0; j < NT; ++j) {
;       const int bsel = j & 1;
;       if (j + 1 < NT) SLOAD(0, (j + 1) * KVBLK);
;       SBAR(); QKT(pA0, pA1, K_lds + bsel * SH::K);
;       PART(pA0, pA1, j, mnA, alA);
;       if constexpr (MODE == 0) RESC(alA);
;       FIN(pA0, pA1, alA); SBAR();
;       pv_d0(o, vb0 + bsel * SH::V, pa0, pa1, pa2, pa3);
;       if (j + 1 < NT) { asm volatile("s_waitcnt vmcnt(0)" ::: "memory"); SWRITE(bsel ^ 1, 0); }
;       __syncthreads();
;     }
	s_cmp_eq_u32 s3, 36
	s_cbranch_scc1 .LBB0_904

; template <int D0> __device__ __forceinline__ void pv_one(f32x16& od, int vb, bf16x8 pa0, bf16x8 pa1, bf16x8 pa2, bf16x8 pa3) {
;   const s16x4 l0 = tr_read<v_rd_off(D0, 0, 0)>(vb), h0 = tr_read<v_rd_off(D0, 0, 1)>(vb), l1 = tr_read<v_rd_off(D0, 1, 0)>(vb), h1 = tr_read<v_rd_off(D0, 1, 1)>(vb);
;   const s16x4 l2 = tr_read<v_rd_off(D0, 2, 0)>(vb), h2 = tr_read<v_rd_off(D0, 2, 1)>(vb), l3 = tr_read<v_rd_off(D0, 3, 0)>(vb), h3 = tr_read<v_rd_off(D0, 3, 1)>(vb);
;   asm volatile("s_waitcnt lgkmcnt(0)" ::: "memory"); SBAR();
;     ...
;   od = __builtin_amdgcn_mfma_f32_32x32x16_bf16(pa0, PK(l0, h0), od, 0, 0, 0);
;   od = __builtin_amdgcn_mfma_f32_32x32x16_bf16(pa1, PK(l1, h1), od, 0, 0, 0);
;   od = __builtin_amdgcn_mfma_f32_32x32x16_bf16(pa2, PK(l2, h2), od, 0, 0, 0);
;   od = __builtin_amdgcn_mfma_f32_32x32x16_bf16(pa3, PK(l3, h3), od, 0, 0, 0);
;     ...
; }
; __device__ __forceinline__ void pv_d0(f32x16* o, int vb, bf16x8 pa0, bf16x8 pa1, bf16x8 pa2, bf16x8 pa3) {
;   pv_one<0>(o[0], vb, pa0, pa1, pa2, pa3); pv_one<1>(o[1], vb, pa0, pa1, pa2, pa3); pv_one<2>(o[2], vb, pa0, pa1, pa2, pa3); pv_one<3>(o[3], vb, pa0, pa1, pa2, pa3);
; }
; template <int DQK>
; __device__ __forceinline__ void partialSM(f32x16& p0, f32x16& p1, float& m_reg, float& mn, float& alpha) {
;     ...
;   if (__builtin_expect(__all(pmax - m_reg <= THR / SCALE), 1)) { mn = m_reg; alpha = 1.f; }
;   else { mn = fmaxf(m_reg, pmax); alpha = __builtin_amdgcn_exp2f((m_reg - mn) * C); m_reg = mn; }
;   const float mnC = -mn * C;
; #pragma unroll
;   for (int r = 0; r < 16; ++r) p0[r] = fmaf(p0[r], C, mnC);
; #pragma unroll
;   for (int r = 0; r < 16; ++r) p1[r] = fmaf(p1[r], C, mnC);
; #pragma unroll
;   for (int r = 0; r < 16; ++r) p0[r] = __builtin_amdgcn_exp2f(p0[r]);
; }
; __device__ __forceinline__ void finishSM(f32x16& p0, f32x16& p1, float alpha, float& l_reg, bf16x8& pa0, bf16x8& pa1, bf16x8& pa2, bf16x8& pa3) {
; #pragma unroll
;   for (int r = 0; r < 16; ++r) p1[r] = __builtin_amdgcn_exp2f(p1[r]);
;   float ps = 0;
; #pragma unroll
;   for (int r = 0; r < 16; ++r) ps += p0[r];
; #pragma unroll
;   for (int r = 0; r < 16; ++r) ps += p1[r];
;   { auto rr = __builtin_amdgcn_permlane32_swap(__float_as_uint(ps), __float_as_uint(ps), false, false);
;     ps = __uint_as_float(rr[0]) + __uint_as_float(rr[1]); }
;   l_reg = l_reg * alpha + ps;
;   pack_p(p0, p1, pa0, pa1, pa2, pa3);
; }
.LBB0_913:
	v_cndmask_b32_e64 v205, v207, v205, s[6:7]
	v_mul_f32_e32 v207, 0xbdd53b94, v205
	v_fmamk_f32 v82, v82, 0x3dd53b94, v207
	v_fmamk_f32 v83, v83, 0x3dd53b94, v207
	v_fmamk_f32 v84, v84, 0x3dd53b94, v207
	v_fmamk_f32 v85, v85, 0x3dd53b94, v207
	v_fmamk_f32 v86, v86, 0x3dd53b94, v207
	v_fmamk_f32 v87, v87, 0x3dd53b94, v207
	v_fmamk_f32 v88, v88, 0x3dd53b94, v207
	v_fmamk_f32 v89, v89, 0x3dd53b94, v207
	v_fmamk_f32 v90, v90, 0x3dd53b94, v207
	v_fmamk_f32 v91, v91, 0x3dd53b94, v207
	v_fmamk_f32 v92, v92, 0x3dd53b94, v207
	v_fmamk_f32 v93, v93, 0x3dd53b94, v207
	v_fmamk_f32 v94, v94, 0x3dd53b94, v207
	v_fmamk_f32 v95, v95, 0x3dd53b94, v207
	v_fmamk_f32 v96, v96, 0x3dd53b94, v207
	v_fmamk_f32 v97, v97, 0x3dd53b94, v207
	v_fmamk_f32 v66, v66, 0x3dd53b94, v207
	v_fmamk_f32 v67, v67, 0x3dd53b94, v207
	v_fmamk_f32 v68, v68, 0x3dd53b94, v207
	v_fmamk_f32 v69, v69, 0x3dd53b94, v207
	v_fmamk_f32 v70, v70, 0x3dd53b94, v207
	v_fmamk_f32 v71, v71, 0x3dd53b94, v207
	v_fmamk_f32 v72, v72, 0x3dd53b94, v207
	v_fmamk_f32 v73, v73, 0x3dd53b94, v207
	v_fmamk_f32 v74, v74, 0x3dd53b94, v207
	v_fmamk_f32 v75, v75, 0x3dd53b94, v207
	v_fmamk_f32 v76, v76, 0x3dd53b94, v207
	v_fmamk_f32 v77, v77, 0x3dd53b94, v207
	v_fmamk_f32 v78, v78, 0x3dd53b94, v207
	v_fmamk_f32 v79, v79, 0x3dd53b94, v207
	v_fmamk_f32 v80, v80, 0x3dd53b94, v207
	v_fmac_f32_e32 v207, 0x3dd53b94, v81
	v_exp_f32_e32 v81, v82
	v_exp_f32_e32 v82, v83
	v_exp_f32_e32 v83, v84
	v_exp_f32_e32 v84, v85
	v_exp_f32_e32 v85, v86
	v_exp_f32_e32 v86, v87
	v_exp_f32_e32 v87, v88
	v_exp_f32_e32 v88, v89
	v_exp_f32_e32 v89, v90
	v_exp_f32_e32 v90, v91
	v_exp_f32_e32 v91, v92
	v_exp_f32_e32 v92, v93
	v_exp_f32_e32 v93, v94
	v_exp_f32_e32 v94, v95
	v_exp_f32_e32 v95, v96
	v_exp_f32_e32 v96, v97
	v_exp_f32_e32 v97, v66
	v_add_f32_e32 v66, 0, v81
	v_add_f32_e32 v66, v82, v66
	v_add_f32_e32 v66, v83, v66
	v_add_f32_e32 v66, v84, v66
	v_add_f32_e32 v66, v85, v66
	v_add_f32_e32 v66, v86, v66
	v_add_f32_e32 v66, v87, v66
	v_add_f32_e32 v66, v88, v66
	v_add_f32_e32 v66, v89, v66
	v_add_f32_e32 v66, v90, v66
	v_add_f32_e32 v66, v91, v66
	v_add_f32_e32 v66, v92, v66
	v_add_f32_e32 v66, v93, v66
	v_exp_f32_e32 v208, v67
	v_add_f32_e32 v66, v94, v66
	v_exp_f32_e32 v209, v68
	v_add_f32_e32 v66, v95, v66
	v_exp_f32_e32 v210, v69
	v_add_f32_e32 v66, v96, v66
	v_exp_f32_e32 v211, v70
	v_add_f32_e32 v66, v97, v66
	v_exp_f32_e32 v212, v71
	v_add_f32_e32 v66, v208, v66
	v_exp_f32_e32 v213, v72
	v_add_f32_e32 v66, v209, v66
	v_exp_f32_e32 v214, v73
	v_add_f32_e32 v66, v210, v66
	v_exp_f32_e32 v215, v74
	v_add_f32_e32 v66, v211, v66
	v_exp_f32_e32 v216, v75
	v_add_f32_e32 v66, v212, v66
	v_exp_f32_e32 v217, v76
	v_add_f32_e32 v66, v213, v66
	v_exp_f32_e32 v218, v77
	v_add_f32_e32 v66, v214, v66
	v_exp_f32_e32 v219, v78
	v_add_f32_e32 v66, v215, v66
	v_exp_f32_e32 v220, v79
	v_add_f32_e32 v66, v216, v66
	v_exp_f32_e32 v221, v80
	v_add_f32_e32 v66, v217, v66
	v_exp_f32_e32 v207, v207
	v_add_f32_e32 v66, v218, v66
	v_add_f32_e32 v66, v219, v66
	v_add_f32_e32 v66, v220, v66
	v_add_f32_e32 v66, v221, v66
	v_add_f32_e32 v66, v207, v66
	v_mov_b32_e32 v67, v66
	s_nop 1
	v_permlane32_swap_b32_e32 v66, v67
	v_cvt_pk_bf16_f32 v68, v81, v82
	v_cvt_pk_bf16_f32 v69, v83, v84
	v_cvt_pk_bf16_f32 v70, v85, v86
	v_cvt_pk_bf16_f32 v71, v87, v88
	v_cvt_pk_bf16_f32 v72, v89, v90
	v_cvt_pk_bf16_f32 v73, v91, v92
	v_cvt_pk_bf16_f32 v74, v93, v94
	v_cvt_pk_bf16_f32 v75, v95, v96
	v_cvt_pk_bf16_f32 v76, v97, v208
	v_cvt_pk_bf16_f32 v77, v209, v210
	v_cvt_pk_bf16_f32 v78, v211, v212
	v_cvt_pk_bf16_f32 v79, v213, v214
	v_cvt_pk_bf16_f32 v80, v215, v216
	v_cvt_pk_bf16_f32 v81, v217, v218
	v_cvt_pk_bf16_f32 v82, v219, v220
	v_cvt_pk_bf16_f32 v83, v221, v207
	v_permlane32_swap_b32_e32 v68, v70
	v_permlane32_swap_b32_e32 v69, v71
	v_permlane32_swap_b32_e32 v72, v74
	v_permlane32_swap_b32_e32 v73, v75
	v_permlane32_swap_b32_e32 v76, v78
	v_permlane32_swap_b32_e32 v77, v79
	v_permlane32_swap_b32_e32 v80, v82
	v_permlane32_swap_b32_e32 v81, v83
	v_lshl_add_u32 v96, s30, 14, v204
	ds_read_b64_tr_b16 v[84:85], v96 offset:0
	ds_read_b64_tr_b16 v[86:87], v96 offset:0x800
	ds_read_b64_tr_b16 v[88:89], v96 offset:0x1000
	ds_read_b64_tr_b16 v[90:91], v96 offset:0x1800
	ds_read_b64_tr_b16 v[92:93], v96 offset:0x2000
	ds_read_b64_tr_b16 v[94:95], v96 offset:0x2800
	ds_read_b64_tr_b16 v[208:209], v96 offset:0x3000
	ds_read_b64_tr_b16 v[210:211], v96 offset:0x3800
	s_waitcnt lgkmcnt(0)
	s_nop 0
	v_mfma_f32_32x32x16_bf16 v[2:17], v[68:71], v[84:87], v[2:17]
	ds_read_b64_tr_b16 v[84:85], v96 offset:0x200
	ds_read_b64_tr_b16 v[86:87], v96 offset:0xa00
	v_mfma_f32_32x32x16_bf16 v[2:17], v[72:75], v[88:91], v[2:17]
	ds_read_b64_tr_b16 v[88:89], v96 offset:0x1200
	ds_read_b64_tr_b16 v[90:91], v96 offset:0x1a00
	v_mfma_f32_32x32x16_bf16 v[2:17], v[76:79], v[92:95], v[2:17]
	ds_read_b64_tr_b16 v[92:93], v96 offset:0x2200
	ds_read_b64_tr_b16 v[94:95], v96 offset:0x2a00
	ds_read_b64_tr_b16 v[212:213], v96 offset:0x3200
	ds_read_b64_tr_b16 v[214:215], v96 offset:0x3a00
	v_mfma_f32_32x32x16_bf16 v[2:17], v[80:83], v[208:211], v[2:17]
	s_waitcnt lgkmcnt(6)
	v_mfma_f32_32x32x16_bf16 v[50:65], v[68:71], v[84:87], v[50:65]
	ds_read_b64_tr_b16 v[84:85], v96 offset:0x400
	ds_read_b64_tr_b16 v[86:87], v96 offset:0xc00
	s_waitcnt lgkmcnt(6)
	v_mfma_f32_32x32x16_bf16 v[50:65], v[72:75], v[88:91], v[50:65]
	ds_read_b64_tr_b16 v[88:89], v96 offset:0x1400
	ds_read_b64_tr_b16 v[90:91], v96 offset:0x1c00
	s_waitcnt lgkmcnt(6)
	v_mfma_f32_32x32x16_bf16 v[50:65], v[76:79], v[92:95], v[50:65]
	ds_read_b64_tr_b16 v[92:93], v96 offset:0x2400
	ds_read_b64_tr_b16 v[94:95], v96 offset:0x2c00
	ds_read_b64_tr_b16 v[208:209], v96 offset:0x3400
	ds_read_b64_tr_b16 v[210:211], v96 offset:0x3c00
	s_waitcnt lgkmcnt(8)
	v_mfma_f32_32x32x16_bf16 v[50:65], v[80:83], v[212:215], v[50:65]
	s_waitcnt lgkmcnt(6)
	v_mfma_f32_32x32x16_bf16 v[34:49], v[68:71], v[84:87], v[34:49]
	ds_read_b64_tr_b16 v[84:85], v96 offset:0x600
	ds_read_b64_tr_b16 v[86:87], v96 offset:0xe00
	s_waitcnt lgkmcnt(6)
	v_mfma_f32_32x32x16_bf16 v[34:49], v[72:75], v[88:91], v[34:49]
	ds_read_b64_tr_b16 v[88:89], v96 offset:0x1600
	ds_read_b64_tr_b16 v[90:91], v96 offset:0x1e00
	s_waitcnt lgkmcnt(6)
	v_mfma_f32_32x32x16_bf16 v[34:49], v[76:79], v[92:95], v[34:49]
	ds_read_b64_tr_b16 v[92:93], v96 offset:0x2600
	ds_read_b64_tr_b16 v[94:95], v96 offset:0x2e00
	ds_read_b64_tr_b16 v[212:213], v96 offset:0x3600
	ds_read_b64_tr_b16 v[214:215], v96 offset:0x3e00
	s_waitcnt lgkmcnt(8)
	v_mfma_f32_32x32x16_bf16 v[34:49], v[80:83], v[208:211], v[34:49]
	s_waitcnt lgkmcnt(6)
	v_mfma_f32_32x32x16_bf16 v[18:33], v[68:71], v[84:87], v[18:33]
	s_andn2_b64 vcc, exec, s[18:19]
	s_waitcnt lgkmcnt(4)
	v_mfma_f32_32x32x16_bf16 v[18:33], v[72:75], v[88:91], v[18:33]
	s_waitcnt lgkmcnt(2)
	v_mfma_f32_32x32x16_bf16 v[18:33], v[76:79], v[92:95], v[18:33]
	s_waitcnt lgkmcnt(0)
	v_mfma_f32_32x32x16_bf16 v[18:33], v[80:83], v[212:215], v[18:33]
	s_cbranch_vccnz .LBB0_915
; #define SWRITE(b, i) do { *(bf16x8*)(V_lds + (b) * SH::V + vst0) = sr_[i].vs0; *(bf16x8*)(V_lds + (b) * SH::V + vst1) = sr_[i].vs1; \
;     _Pragma("unroll") for (int q_ = 0; q_ < KPT; ++q_) *(bf16x8*)(K_lds + (b) * SH::K + KSWZ(krow[q_], kcol[q_] * 2)) = sr_[i].ks[q_]; } while (0)
; template <int DQK, int MODE, int SDEPTH, int ldq, int ldk, int ldv, int ldo, int ldg> ...
;     ...
;       if (j + 1 < NT) { asm volatile("s_waitcnt vmcnt(0)" ::: "memory"); SWRITE(bsel ^ 1, 0); }
	s_xor_b32 s6, s30, 1
	s_lshl_b32 s7, s6, 14
	s_add_i32 s7, s7, 0
	v_add_u32_e32 v68, s7, v183
	s_lshl_b32 s6, s6, 13
	s_waitcnt vmcnt(0)
	ds_write_b128 v68, v[98:101]
	v_add_u32_e32 v68, s7, v182
	s_add_i32 s7, s7, s6
	ds_write_b128 v68, v[102:105]
	v_add3_u32 v68, s7, v184, v185
	ds_write_b128 v68, v[106:109] offset:32768
	v_add3_u32 v68, s7, v186, v187
	ds_write_b128 v68, v[110:113] offset:32768
	v_add3_u32 v68, s7, v188, v189
	ds_write_b128 v68, v[146:149] offset:32768

; #define SBAR() __builtin_amdgcn_sched_barrier(0)
; #define SLOAD(i, k0) do { sr_[i].vs0 = *reinterpret_cast<const bf16x8*>(&Vh[(long)((k0) + sr) * ldv + sc]); sr_[i].vs1 = *reinterpret_cast<const bf16x8*>(&Vh[(long)((k0) + 32 + sr) * ldv + sc]); \
;     _Pragma("unroll") for (int q_ = 0; q_ < KPT; ++q_) sr_[i].ks[q_] = *reinterpret_cast<const bf16x8*>(&Kh[(long)((k0) + krow[q_]) * ldk + kcol[q_]]); } while (0)
; #define PART(P0, P1, tj, MN, AL) do { if constexpr (MODE == 0) partialSM<DQK>(P0, P1, m_reg, MN, AL); else ret_weights(P0, P1, TKIND(tj), nlane - (float)(64 * (tj) - 256), lf2, lb2); } while (0)
; #define FIN(P0, P1, AL) do { if constexpr (MODE == 0) finishSM(P0, P1, AL, l_reg, pa0, pa1, pa2, pa3); else pack_p(P0, P1, pa0, pa1, pa2, pa3); } while (0)
; __device__ __forceinline__ void finishSM(f32x16& p0, f32x16& p1, float alpha, float& l_reg, bf16x8& pa0, bf16x8& pa1, bf16x8& pa2, bf16x8& pa3) {
; #pragma unroll
;   for (int r = 0; r < 16; ++r) p1[r] = __builtin_amdgcn_exp2f(p1[r]);
;   float ps = 0;
; #pragma unroll
;   for (int r = 0; r < 16; ++r) ps += p0[r];
; #pragma unroll
;   for (int r = 0; r < 16; ++r) ps += p1[r];
;   { auto rr = __builtin_amdgcn_permlane32_swap(__float_as_uint(ps), __float_as_uint(ps), false, false);
;     ps = __uint_as_float(rr[0]) + __uint_as_float(rr[1]); }
;   l_reg = l_reg * alpha + ps;
;   pack_p(p0, p1, pa0, pa1, pa2, pa3);
; }
; template <int DQK, int MODE, int SDEPTH, int ldq, int ldk, int ldv, int ldo, int ldg> ...
;     ...
;       SBAR(); QKT(pB0, pB1, K_lds + SH::K);
;       FIN(pA0, pA1, alA); SBAR();
;       SLOAD(SO, (j + SDEPTH) * KVBLK); SBAR();
;       pv_d0(o, vb0, pa0, pa1, pa2, pa3); PART(pB0, pB1, j, mnB, alB);
.LBB0_1920:
	ds_read_b128 v[66:69], v177 offset:49152
	ds_read_b128 v[82:85], v177 offset:57344
	ds_read_b128 v[86:89], v178 offset:49152
	ds_read_b128 v[204:207], v178 offset:57344
	ds_read_b128 v[90:93], v179 offset:49152
	ds_read_b128 v[208:211], v179 offset:57344
	ds_read_b128 v[94:97], v180 offset:49152
	ds_read_b128 v[212:215], v180 offset:57344
	s_waitcnt lgkmcnt(7)
	v_mfma_f32_32x32x16_bf16 v[66:81], v[66:69], v[126:129], 0
	ds_read_b128 v[188:191], v181 offset:49152
	ds_read_b128 v[216:219], v181 offset:57344
	ds_read_b128 v[220:223], v182 offset:49152
	ds_read_b128 v[226:229], v182 offset:57344
	ds_read_b128 v[230:233], v183 offset:49152
	ds_read_b128 v[234:237], v183 offset:57344
	ds_read_b128 v[238:241], v184 offset:49152
	ds_read_b128 v[242:245], v184 offset:57344
	s_waitcnt lgkmcnt(13)
	v_mfma_f32_32x32x16_bf16 v[66:81], v[86:89], v[122:125], v[66:81]
	v_exp_f32_e32 v86, v142
	v_exp_f32_e32 v87, v143
	v_exp_f32_e32 v88, v140
	v_exp_f32_e32 v89, v141
	v_exp_f32_e32 v140, v136
	v_exp_f32_e32 v141, v137
	v_exp_f32_e32 v142, v132
	s_waitcnt lgkmcnt(11)
	v_mfma_f32_32x32x16_bf16 v[66:81], v[90:93], v[118:121], v[66:81]
	v_exp_f32_e32 v90, v133
	v_exp_f32_e32 v91, v130
	v_exp_f32_e32 v92, v131
	v_exp_f32_e32 v93, v144
	v_exp_f32_e32 v143, v145
	v_exp_f32_e32 v144, v138
	v_exp_f32_e32 v145, v139
	s_waitcnt lgkmcnt(9)
	v_mfma_f32_32x32x16_bf16 v[66:81], v[94:97], v[114:117], v[66:81]
	v_add_f32_e32 v96, 0, v195
	v_add_f32_e32 v96, v196, v96
	v_add_f32_e32 v96, v197, v96
	v_add_f32_e32 v96, v198, v96
	v_add_f32_e32 v96, v199, v96
	v_add_f32_e32 v96, v201, v96
	v_add_f32_e32 v96, v200, v96
	s_waitcnt lgkmcnt(7)
	v_mfma_f32_32x32x16_bf16 v[66:81], v[188:191], v[110:113], v[66:81]
	v_add_f32_e32 v96, v202, v96
	v_add_f32_e32 v96, v159, v96
	v_add_f32_e32 v96, v160, v96
	v_add_f32_e32 v96, v161, v96
	v_add_f32_e32 v96, v163, v96
	v_add_f32_e32 v96, v162, v96
	v_add_f32_e32 v96, v192, v96
	s_waitcnt lgkmcnt(5)
	v_mfma_f32_32x32x16_bf16 v[66:81], v[220:223], v[106:109], v[66:81]
	v_add_f32_e32 v96, v193, v96
	v_add_f32_e32 v96, v194, v96
	v_add_f32_e32 v96, v86, v96
	v_add_f32_e32 v96, v87, v96
	v_add_f32_e32 v96, v88, v96
	v_add_f32_e32 v96, v89, v96
	v_add_f32_e32 v96, v140, v96
	s_waitcnt lgkmcnt(3)
	v_mfma_f32_32x32x16_bf16 v[66:81], v[230:233], v[102:105], v[66:81]
	v_add_f32_e32 v96, v141, v96
	v_add_f32_e32 v96, v142, v96
	v_add_f32_e32 v96, v90, v96
	v_add_f32_e32 v96, v91, v96
	v_add_f32_e32 v96, v92, v96
	v_exp_f32_e32 v94, v134
	v_add_f32_e32 v96, v93, v96
	s_waitcnt lgkmcnt(1)
	v_mfma_f32_32x32x16_bf16 v[66:81], v[238:241], v[98:101], v[66:81]
	v_exp_f32_e32 v95, v135
	v_add_f32_e32 v96, v143, v96
	v_add_f32_e32 v96, v144, v96
	v_add_f32_e32 v96, v145, v96
	v_add_f32_e32 v96, v94, v96
	v_add_f32_e32 v187, v95, v96
	v_mov_b32_e32 v188, v187
	v_cvt_pk_bf16_f32 v130, v195, v196
	v_cvt_pk_bf16_f32 v132, v199, v201
	v_permlane32_swap_b32_e32 v187, v188
	v_cvt_pk_bf16_f32 v131, v197, v198
	v_cvt_pk_bf16_f32 v133, v200, v202
	v_permlane32_swap_b32_e32 v130, v132
	v_cvt_pk_bf16_f32 v134, v159, v160
	v_cvt_pk_bf16_f32 v135, v161, v163
	v_cvt_pk_bf16_f32 v136, v162, v192
	v_cvt_pk_bf16_f32 v137, v193, v194
	v_cvt_pk_bf16_f32 v138, v86, v87
	v_cvt_pk_bf16_f32 v139, v88, v89
	v_cvt_pk_bf16_f32 v140, v140, v141
	v_cvt_pk_bf16_f32 v141, v142, v90
	v_cvt_pk_bf16_f32 v142, v91, v92
	v_cvt_pk_bf16_f32 v143, v93, v143
	v_cvt_pk_bf16_f32 v144, v144, v145
	v_cvt_pk_bf16_f32 v145, v94, v95
	v_permlane32_swap_b32_e32 v131, v133
	v_permlane32_swap_b32_e32 v134, v136
	v_permlane32_swap_b32_e32 v135, v137
	v_permlane32_swap_b32_e32 v138, v140
	v_permlane32_swap_b32_e32 v139, v141
	v_permlane32_swap_b32_e32 v142, v144
	v_permlane32_swap_b32_e32 v143, v145
	v_lshl_add_u64 v[158:159], v[152:153], 0, s[38:39]
	v_mfma_f32_32x32x16_bf16 v[82:97], v[82:85], v[126:129], 0
	v_add_co_u32_e32 v162, vcc, s63, v158
	v_lshl_add_u64 v[160:161], v[156:157], 0, s[38:39]
	s_nop 0
	v_addc_co_u32_e32 v163, vcc, 0, v159, vcc
	v_add_co_u32_e32 v194, vcc, s64, v158
	v_mfma_f32_32x32x16_bf16 v[82:97], v[204:207], v[122:125], v[82:97]
	s_nop 0
	v_addc_co_u32_e32 v195, vcc, 0, v159, vcc
	v_add_co_u32_e32 v198, vcc, s65, v160
	global_load_dwordx4 v[190:193], v[162:163], off
	s_nop 0
	global_load_dwordx4 v[194:197], v[194:195], off
	v_addc_co_u32_e32 v199, vcc, 0, v161, vcc
	v_lshl_add_u64 v[162:163], v[154:155], 0, s[38:39]
	v_add_co_u32_e32 v202, vcc, s65, v162
	global_load_dwordx4 v[198:201], v[198:199], off
	s_nop 0
	v_addc_co_u32_e32 v203, vcc, 0, v163, vcc
	global_load_dwordx4 v[202:205], v[202:203], off
	v_mfma_f32_32x32x16_bf16 v[82:97], v[208:211], v[118:121], v[82:97]
	v_mfma_f32_32x32x16_bf16 v[82:97], v[212:215], v[114:117], v[82:97]
	v_mfma_f32_32x32x16_bf16 v[82:97], v[216:219], v[110:113], v[82:97]
	v_mfma_f32_32x32x16_bf16 v[82:97], v[226:229], v[106:109], v[82:97]
	v_mfma_f32_32x32x16_bf16 v[82:97], v[234:237], v[102:105], v[82:97]
	s_waitcnt lgkmcnt(0)
	v_mfma_f32_32x32x16_bf16 v[82:97], v[242:245], v[98:101], v[82:97]
	ds_read_b64_tr_b16 v[206:207], v172 offset:0
	ds_read_b64_tr_b16 v[208:209], v172 offset:0x800
	ds_read_b64_tr_b16 v[210:211], v172 offset:0x1000
	ds_read_b64_tr_b16 v[212:213], v172 offset:0x1800
	ds_read_b64_tr_b16 v[214:215], v172 offset:0x2000
	ds_read_b64_tr_b16 v[216:217], v172 offset:0x2800
	ds_read_b64_tr_b16 v[218:219], v172 offset:0x3000
	ds_read_b64_tr_b16 v[220:221], v172 offset:0x3800
	s_waitcnt lgkmcnt(0)
; #define SBAR() __builtin_amdgcn_sched_barrier(0)
; template <int OFF> __device__ __forceinline__ s16x4 tr_read(int vb) { s16x4 r; asm volatile("ds_read_b64_tr_b16 %0, %1 offset:%2" : "=&v"(r) : "v"(vb), "i"(OFF) : "memory"); return r; }
; template <int D0> __device__ __forceinline__ void pv_one(f32x16& od, int vb, bf16x8 pa0, bf16x8 pa1, bf16x8 pa2, bf16x8 pa3) {
;   const s16x4 l0 = tr_read<v_rd_off(D0, 0, 0)>(vb), h0 = tr_read<v_rd_off(D0, 0, 1)>(vb), l1 = tr_read<v_rd_off(D0, 1, 0)>(vb), h1 = tr_read<v_rd_off(D0, 1, 1)>(vb);
;   const s16x4 l2 = tr_read<v_rd_off(D0, 2, 0)>(vb), h2 = tr_read<v_rd_off(D0, 2, 1)>(vb), l3 = tr_read<v_rd_off(D0, 3, 0)>(vb), h3 = tr_read<v_rd_off(D0, 3, 1)>(vb);
;   asm volatile("s_waitcnt lgkmcnt(0)" ::: "memory"); SBAR();
;     ...
;   od = __builtin_amdgcn_mfma_f32_32x32x16_bf16(pa0, PK(l0, h0), od, 0, 0, 0);
;   od = __builtin_amdgcn_mfma_f32_32x32x16_bf16(pa1, PK(l1, h1), od, 0, 0, 0);
;   od = __builtin_amdgcn_mfma_f32_32x32x16_bf16(pa2, PK(l2, h2), od, 0, 0, 0);
;   od = __builtin_amdgcn_mfma_f32_32x32x16_bf16(pa3, PK(l3, h3), od, 0, 0, 0);
;     ...
; }
; __device__ __forceinline__ void pv_d0(f32x16* o, int vb, bf16x8 pa0, bf16x8 pa1, bf16x8 pa2, bf16x8 pa3) {
;   pv_one<0>(o[0], vb, pa0, pa1, pa2, pa3); pv_one<1>(o[1], vb, pa0, pa1, pa2, pa3); pv_one<2>(o[2], vb, pa0, pa1, pa2, pa3); pv_one<3>(o[3], vb, pa0, pa1, pa2, pa3);
; }
; template <int DQK>
; __device__ __forceinline__ void partialSM(f32x16& p0, f32x16& p1, float& m_reg, float& mn, float& alpha) {
;     ...
;   float pmax = p0[0];
; #pragma unroll
;   for (int r = 1; r < 16; ++r) pmax = fmaxf(pmax, p0[r]);
; #pragma unroll
;   for (int r = 0; r < 16; ++r) pmax = fmaxf(pmax, p1[r]);
;   { auto rr = __builtin_amdgcn_permlane32_swap(__float_as_uint(pmax), __float_as_uint(pmax), false, false);
;     pmax = fmaxf(__uint_as_float(rr[0]), __uint_as_float(rr[1])); }
;   if (__builtin_expect(__all(pmax - m_reg <= THR / SCALE), 1)) { mn = m_reg; alpha = 1.f; }
;   else { mn = fmaxf(m_reg, pmax); alpha = __builtin_amdgcn_exp2f((m_reg - mn) * C); m_reg = mn; }
	s_nop 0
	v_mfma_f32_32x32x16_bf16 v[2:17], v[130:133], v[206:209], v[2:17]
	ds_read_b64_tr_b16 v[206:207], v172 offset:0x200
	ds_read_b64_tr_b16 v[208:209], v172 offset:0xa00
	v_mfma_f32_32x32x16_bf16 v[2:17], v[134:137], v[210:213], v[2:17]
	ds_read_b64_tr_b16 v[210:211], v172 offset:0x1200
	ds_read_b64_tr_b16 v[212:213], v172 offset:0x1a00
	v_mfma_f32_32x32x16_bf16 v[2:17], v[138:141], v[214:217], v[2:17]
	ds_read_b64_tr_b16 v[214:215], v172 offset:0x2200
	ds_read_b64_tr_b16 v[216:217], v172 offset:0x2a00
	ds_read_b64_tr_b16 v[226:227], v172 offset:0x3200
	ds_read_b64_tr_b16 v[228:229], v172 offset:0x3a00
	v_mfma_f32_32x32x16_bf16 v[2:17], v[142:145], v[218:221], v[2:17]
	s_waitcnt lgkmcnt(6)
	v_mfma_f32_32x32x16_bf16 v[50:65], v[130:133], v[206:209], v[50:65]
	ds_read_b64_tr_b16 v[206:207], v172 offset:0x400
	ds_read_b64_tr_b16 v[208:209], v172 offset:0xc00
	s_waitcnt lgkmcnt(6)
	v_mfma_f32_32x32x16_bf16 v[50:65], v[134:137], v[210:213], v[50:65]
	ds_read_b64_tr_b16 v[210:211], v172 offset:0x1400
	ds_read_b64_tr_b16 v[212:213], v172 offset:0x1c00
	s_waitcnt lgkmcnt(6)
	v_mfma_f32_32x32x16_bf16 v[50:65], v[138:141], v[214:217], v[50:65]
	ds_read_b64_tr_b16 v[214:215], v172 offset:0x2400
	ds_read_b64_tr_b16 v[216:217], v172 offset:0x2c00
	ds_read_b64_tr_b16 v[218:219], v172 offset:0x3400
	ds_read_b64_tr_b16 v[220:221], v172 offset:0x3c00
	s_waitcnt lgkmcnt(8)
	v_mfma_f32_32x32x16_bf16 v[50:65], v[142:145], v[226:229], v[50:65]
	s_waitcnt lgkmcnt(6)
	v_mfma_f32_32x32x16_bf16 v[34:49], v[130:133], v[206:209], v[34:49]
	ds_read_b64_tr_b16 v[206:207], v172 offset:0x600
	ds_read_b64_tr_b16 v[208:209], v172 offset:0xe00
	s_waitcnt lgkmcnt(6)
	v_mfma_f32_32x32x16_bf16 v[34:49], v[134:137], v[210:213], v[34:49]
	ds_read_b64_tr_b16 v[210:211], v172 offset:0x1600
	ds_read_b64_tr_b16 v[212:213], v172 offset:0x1e00
	s_waitcnt lgkmcnt(6)
	v_mfma_f32_32x32x16_bf16 v[34:49], v[138:141], v[214:217], v[34:49]
	ds_read_b64_tr_b16 v[214:215], v172 offset:0x2600
	ds_read_b64_tr_b16 v[216:217], v172 offset:0x2e00
	ds_read_b64_tr_b16 v[226:227], v172 offset:0x3600
	ds_read_b64_tr_b16 v[228:229], v172 offset:0x3e00
	s_waitcnt lgkmcnt(8)
	v_mfma_f32_32x32x16_bf16 v[34:49], v[142:145], v[218:221], v[34:49]
	v_max_f32_e32 v189, v67, v67
	v_max_f32_e32 v218, v66, v66
	s_waitcnt lgkmcnt(6)
	v_mfma_f32_32x32x16_bf16 v[18:33], v[130:133], v[206:209], v[18:33]
	v_max_f32_e32 v189, v218, v189
	v_max3_f32 v189, v189, v68, v69
	v_max3_f32 v189, v189, v70, v71
	v_max3_f32 v130, v189, v72, v73
	v_max3_f32 v130, v130, v74, v75
	v_max3_f32 v130, v130, v76, v77
	v_max3_f32 v130, v130, v78, v79
	v_max3_f32 v130, v130, v80, v81
	s_waitcnt lgkmcnt(4)
	v_mfma_f32_32x32x16_bf16 v[18:33], v[134:137], v[210:213], v[18:33]
	v_max3_f32 v130, v130, v82, v83
	v_max3_f32 v130, v130, v84, v85
	v_max3_f32 v130, v130, v86, v87
	v_max3_f32 v130, v130, v88, v89
	v_max3_f32 v130, v130, v90, v91
	v_max3_f32 v130, v130, v92, v93
	v_max3_f32 v130, v130, v94, v95
	v_max3_f32 v130, v130, v96, v97
	s_waitcnt lgkmcnt(2)
	v_mfma_f32_32x32x16_bf16 v[18:33], v[138:141], v[214:217], v[18:33]
	v_mov_b32_e32 v131, v130
	s_nop 1
	v_permlane32_swap_b32_e32 v130, v131
	v_max_f32_e32 v131, v131, v131
	v_max_f32_e32 v130, v130, v130
	v_max_f32_e32 v130, v130, v131
	v_sub_f32_e32 v131, v130, v186
	v_cmp_ge_f32_e32 vcc, s60, v131
	v_max_f32_e32 v131, v186, v186
	v_max_f32_e32 v130, v131, v130
	s_waitcnt lgkmcnt(0)
	v_mfma_f32_32x32x16_bf16 v[18:33], v[142:145], v[226:229], v[18:33]
	v_sub_f32_e32 v131, v186, v130
	v_mul_f32_e32 v131, 0x3e0293ee, v131
	v_exp_f32_e32 v131, v131
	s_cmp_eq_u64 vcc, exec
	s_barrier
	s_waitcnt vmcnt(0)
	s_cselect_b64 s[6:7], -1, 0
	v_cndmask_b32_e64 v189, v131, 1.0, s[6:7]
	v_cmp_gt_f32_e32 vcc, 1.0, v189
	s_waitcnt vmcnt(3)
	ds_write_b128 v173, v[190:193]
	s_waitcnt vmcnt(2)
	ds_write_b128 v174, v[194:197]
	s_waitcnt vmcnt(1)
	ds_write_b128 v175, v[198:201] offset:32768
	s_waitcnt vmcnt(0)
	ds_write_b128 v176, v[202:205] offset:32768
	s_cbranch_vccz .LBB0_1924
	s_and_saveexec_b64 s[54:55], s[4:5]
	ds_write_b32 v168, v189 offset:128
	s_or_b64 exec, exec, s[54:55]
	s_waitcnt lgkmcnt(0)
	v_add_u32_e32 v131, v151, v146
	ds_read_b128 v[132:135], v131 offset:224
	ds_read_b128 v[136:139], v131 offset:192
	ds_read_b128 v[140:143], v131 offset:160
	ds_read_b128 v[190:193], v131 offset:128
	s_waitcnt lgkmcnt(3)
	v_pk_mul_f32 v[14:15], v[14:15], v[132:133]
	s_waitcnt lgkmcnt(2)
	v_pk_mul_f32 v[10:11], v[10:11], v[136:137]
	s_waitcnt lgkmcnt(1)
	v_pk_mul_f32 v[6:7], v[6:7], v[140:141]
	v_pk_mul_f32 v[16:17], v[16:17], v[134:135]
	v_pk_mul_f32 v[12:13], v[12:13], v[138:139]
	v_pk_mul_f32 v[8:9], v[8:9], v[142:143]
	s_waitcnt lgkmcnt(0)
	v_pk_mul_f32 v[4:5], v[4:5], v[192:193]
	v_pk_mul_f32 v[2:3], v[2:3], v[190:191]
	v_pk_mul_f32 v[62:63], v[62:63], v[132:133]
	v_pk_mul_f32 v[58:59], v[58:59], v[136:137]
	v_pk_mul_f32 v[54:55], v[54:55], v[140:141]
	v_pk_mul_f32 v[64:65], v[64:65], v[134:135]
	v_pk_mul_f32 v[60:61], v[60:61], v[138:139]
	v_pk_mul_f32 v[56:57], v[56:57], v[142:143]
	v_pk_mul_f32 v[52:53], v[52:53], v[192:193]
	v_pk_mul_f32 v[50:51], v[50:51], v[190:191]
	v_pk_mul_f32 v[46:47], v[46:47], v[132:133]
	v_pk_mul_f32 v[42:43], v[42:43], v[136:137]
	v_pk_mul_f32 v[38:39], v[38:39], v[140:141]
	v_pk_mul_f32 v[48:49], v[48:49], v[134:135]
	v_pk_mul_f32 v[44:45], v[44:45], v[138:139]
	v_pk_mul_f32 v[40:41], v[40:41], v[142:143]
	v_pk_mul_f32 v[36:37], v[36:37], v[192:193]
	v_pk_mul_f32 v[34:35], v[34:35], v[190:191]
	v_pk_mul_f32 v[30:31], v[30:31], v[132:133]
	v_pk_mul_f32 v[26:27], v[26:27], v[136:137]
	v_pk_mul_f32 v[22:23], v[22:23], v[140:141]
	v_pk_mul_f32 v[32:33], v[32:33], v[134:135]
	v_pk_mul_f32 v[28:29], v[28:29], v[138:139]
	v_pk_mul_f32 v[24:25], v[24:25], v[142:143]
	v_pk_mul_f32 v[20:21], v[20:21], v[192:193]
	v_pk_mul_f32 v[18:19], v[18:19], v[190:191]
; template <int DQK>
; __device__ __forceinline__ void partialSM(f32x16& p0, f32x16& p1, float& m_reg, float& mn, float& alpha) {
;     ...
;   const float mnC = -mn * C;
; #pragma unroll
;   for (int r = 0; r < 16; ++r) p0[r] = fmaf(p0[r], C, mnC);
; #pragma unroll
;   for (int r = 0; r < 16; ++r) p1[r] = fmaf(p1[r], C, mnC);
; #pragma unroll
;   for (int r = 0; r < 16; ++r) p0[r] = __builtin_amdgcn_exp2f(p0[r]);
; }
; __device__ __forceinline__ void finishSM(f32x16& p0, f32x16& p1, float alpha, float& l_reg, bf16x8& pa0, bf16x8& pa1, bf16x8& pa2, bf16x8& pa3) {
; #pragma unroll
;   for (int r = 0; r < 16; ++r) p1[r] = __builtin_amdgcn_exp2f(p1[r]);
;   float ps = 0;
; #pragma unroll
;   for (int r = 0; r < 16; ++r) ps += p0[r];
; #pragma unroll
;   for (int r = 0; r < 16; ++r) ps += p1[r];
;   { auto rr = __builtin_amdgcn_permlane32_swap(__float_as_uint(ps), __float_as_uint(ps), false, false);
;     ps = __uint_as_float(rr[0]) + __uint_as_float(rr[1]); }
;   l_reg = l_reg * alpha + ps;
;   pack_p(p0, p1, pa0, pa1, pa2, pa3);
; }
.LBB0_1924:
	v_cndmask_b32_e64 v130, v130, v186, s[6:7]
	v_mul_f32_e32 v142, 0xbe0293ee, v130
	v_fmamk_f32 v66, v66, 0x3e0293ee, v142
	v_fmamk_f32 v74, v74, 0x3e0293ee, v142
	v_fmamk_f32 v75, v75, 0x3e0293ee, v142
	v_fmamk_f32 v76, v76, 0x3e0293ee, v142
	v_fmamk_f32 v77, v77, 0x3e0293ee, v142
	v_fmamk_f32 v78, v78, 0x3e0293ee, v142
	v_fmamk_f32 v190, v82, 0x3e0293ee, v142
	v_fmamk_f32 v186, v84, 0x3e0293ee, v142
	v_fmamk_f32 v145, v86, 0x3e0293ee, v142
	v_fmamk_f32 v144, v88, 0x3e0293ee, v142
	v_fmamk_f32 v143, v90, 0x3e0293ee, v142
	v_exp_f32_e32 v88, v66
	v_exp_f32_e32 v82, v74
	v_exp_f32_e32 v84, v75
	v_exp_f32_e32 v86, v76
	v_exp_f32_e32 v90, v77
	v_exp_f32_e32 v131, v78
	v_fmamk_f32 v67, v67, 0x3e0293ee, v142
	v_fmamk_f32 v68, v68, 0x3e0293ee, v142
	v_fmamk_f32 v69, v69, 0x3e0293ee, v142
	v_fmamk_f32 v70, v70, 0x3e0293ee, v142
	v_fmamk_f32 v71, v71, 0x3e0293ee, v142
	v_fmamk_f32 v72, v72, 0x3e0293ee, v142
	v_fmamk_f32 v73, v73, 0x3e0293ee, v142
	v_fmamk_f32 v79, v79, 0x3e0293ee, v142
	v_fmamk_f32 v80, v80, 0x3e0293ee, v142
	v_fmamk_f32 v81, v81, 0x3e0293ee, v142
	v_fmamk_f32 v191, v92, 0x3e0293ee, v142
	v_fmamk_f32 v94, v94, 0x3e0293ee, v142
	v_fmamk_f32 v92, v96, 0x3e0293ee, v142
	v_fmamk_f32 v83, v83, 0x3e0293ee, v142
	v_fmamk_f32 v85, v85, 0x3e0293ee, v142
	v_fmamk_f32 v87, v87, 0x3e0293ee, v142
	v_fmamk_f32 v89, v89, 0x3e0293ee, v142
	v_fmamk_f32 v91, v91, 0x3e0293ee, v142
	v_fmamk_f32 v93, v93, 0x3e0293ee, v142
	v_fmamk_f32 v95, v95, 0x3e0293ee, v142
	v_exp_f32_e32 v132, v67
	v_exp_f32_e32 v133, v68
	v_exp_f32_e32 v136, v69
	v_exp_f32_e32 v137, v70
	v_exp_f32_e32 v139, v71
	v_exp_f32_e32 v140, v72
	v_exp_f32_e32 v141, v73
	v_exp_f32_e32 v134, v79
	v_exp_f32_e32 v135, v80
	v_exp_f32_e32 v138, v81
	v_fmac_f32_e32 v142, 0x3e0293ee, v97
	s_waitcnt lgkmcnt(0)
	s_barrier
	ds_read_b128 v[66:69], v177 offset:32768
	ds_read_b128 v[192:195], v177 offset:40960
	ds_read_b128 v[196:199], v178 offset:32768
	ds_read_b128 v[200:203], v178 offset:40960
	ds_read_b128 v[204:207], v179 offset:32768
	ds_read_b128 v[208:211], v179 offset:40960
	ds_read_b128 v[212:215], v180 offset:32768
	ds_read_b128 v[216:219], v180 offset:40960
	s_waitcnt lgkmcnt(7)
	v_mfma_f32_32x32x16_bf16 v[66:81], v[66:69], v[126:129], 0
	ds_read_b128 v[220:223], v181 offset:32768
	ds_read_b128 v[226:229], v181 offset:40960
	ds_read_b128 v[230:233], v182 offset:32768
	ds_read_b128 v[234:237], v182 offset:40960
	ds_read_b128 v[238:241], v183 offset:32768
	ds_read_b128 v[242:245], v183 offset:40960
	ds_read_b128 v[246:249], v184 offset:32768
	ds_read_b128 v[250:253], v184 offset:40960
	v_exp_f32_e32 v96, v190
	v_exp_f32_e32 v83, v83
	v_exp_f32_e32 v97, v186
	v_exp_f32_e32 v85, v85
	v_exp_f32_e32 v186, v145
	v_exp_f32_e32 v87, v87
	s_waitcnt lgkmcnt(13)
	v_mfma_f32_32x32x16_bf16 v[66:81], v[196:199], v[122:125], v[66:81]
	v_exp_f32_e32 v199, v142
	v_add_f32_e32 v142, 0, v88
	v_add_f32_e32 v142, v132, v142
	v_add_f32_e32 v142, v133, v142
	v_add_f32_e32 v142, v136, v142
	v_add_f32_e32 v142, v137, v142
	v_add_f32_e32 v142, v139, v142
	s_waitcnt lgkmcnt(11)
	v_mfma_f32_32x32x16_bf16 v[66:81], v[204:207], v[118:121], v[66:81]
	v_add_f32_e32 v142, v140, v142
	v_add_f32_e32 v142, v141, v142
	v_add_f32_e32 v142, v82, v142
	v_add_f32_e32 v142, v84, v142
	v_add_f32_e32 v142, v86, v142
	v_add_f32_e32 v142, v90, v142
	v_add_f32_e32 v142, v131, v142
	s_waitcnt lgkmcnt(9)
	v_mfma_f32_32x32x16_bf16 v[66:81], v[212:215], v[114:117], v[66:81]
	v_add_f32_e32 v142, v134, v142
	v_add_f32_e32 v142, v135, v142
	v_add_f32_e32 v142, v138, v142
	v_add_f32_e32 v142, v96, v142
	v_add_f32_e32 v142, v83, v142
	v_exp_f32_e32 v196, v144
	v_add_f32_e32 v142, v97, v142
	s_waitcnt lgkmcnt(7)
	v_mfma_f32_32x32x16_bf16 v[66:81], v[220:223], v[110:113], v[66:81]
	v_exp_f32_e32 v89, v89
	v_add_f32_e32 v142, v85, v142
	v_exp_f32_e32 v197, v143
	v_add_f32_e32 v142, v186, v142
	v_exp_f32_e32 v91, v91
	v_add_f32_e32 v142, v87, v142
	v_exp_f32_e32 v198, v191
	s_waitcnt lgkmcnt(5)
	v_mfma_f32_32x32x16_bf16 v[66:81], v[230:233], v[106:109], v[66:81]
	v_add_f32_e32 v142, v196, v142
	v_exp_f32_e32 v93, v93
	v_add_f32_e32 v142, v89, v142
	v_exp_f32_e32 v94, v94
	v_add_f32_e32 v142, v197, v142
	v_exp_f32_e32 v95, v95
	v_add_f32_e32 v142, v91, v142
	s_waitcnt lgkmcnt(3)
	v_mfma_f32_32x32x16_bf16 v[66:81], v[238:241], v[102:105], v[66:81]
	v_exp_f32_e32 v92, v92
	v_add_f32_e32 v142, v198, v142
	v_add_f32_e32 v142, v93, v142
	v_add_f32_e32 v142, v94, v142
	v_add_f32_e32 v142, v95, v142
	v_add_f32_e32 v142, v92, v142
	v_add_f32_e32 v190, v199, v142
	s_waitcnt lgkmcnt(1)
	v_mfma_f32_32x32x16_bf16 v[66:81], v[246:249], v[98:101], v[66:81]
	v_mov_b32_e32 v191, v190
	s_nop 1
	v_permlane32_swap_b32_e32 v190, v191
	v_cvt_pk_bf16_f32 v142, v88, v132
	v_cvt_pk_bf16_f32 v143, v133, v136
	v_cvt_pk_bf16_f32 v144, v137, v139
	v_cvt_pk_bf16_f32 v145, v140, v141
	v_cvt_pk_bf16_f32 v132, v82, v84
	v_cvt_pk_bf16_f32 v133, v86, v90
	v_cvt_pk_bf16_f32 v134, v131, v134
	v_cvt_pk_bf16_f32 v135, v135, v138
	v_cvt_pk_bf16_f32 v136, v96, v83
	v_cvt_pk_bf16_f32 v137, v97, v85
	v_cvt_pk_bf16_f32 v138, v186, v87
	v_cvt_pk_bf16_f32 v139, v196, v89
	v_cvt_pk_bf16_f32 v196, v197, v91
	v_cvt_pk_bf16_f32 v197, v198, v93
	v_cvt_pk_bf16_f32 v198, v94, v95
	v_cvt_pk_bf16_f32 v199, v92, v199
	v_permlane32_swap_b32_e32 v142, v144
	v_permlane32_swap_b32_e32 v143, v145
	v_permlane32_swap_b32_e32 v132, v134
	v_permlane32_swap_b32_e32 v133, v135
	v_permlane32_swap_b32_e32 v136, v138
	v_permlane32_swap_b32_e32 v137, v139
	v_permlane32_swap_b32_e32 v196, v198
	v_permlane32_swap_b32_e32 v197, v199
	v_mfma_f32_32x32x16_bf16 v[82:97], v[192:195], v[126:129], 0
	v_add_co_u32_e32 v140, vcc, s68, v158
	s_nop 1
	v_addc_co_u32_e32 v141, vcc, 0, v159, vcc
	v_add_co_u32_e32 v158, vcc, s69, v158
	v_mfma_f32_32x32x16_bf16 v[82:97], v[200:203], v[122:125], v[82:97]
	s_nop 0
	v_addc_co_u32_e32 v159, vcc, 0, v159, vcc
	global_load_dwordx4 v[192:195], v[140:141], off
	global_load_dwordx4 v[200:203], v[158:159], off
	v_add_co_u32_e32 v140, vcc, s70, v160
	s_nop 1
	v_addc_co_u32_e32 v141, vcc, 0, v161, vcc
	v_add_co_u32_e32 v162, vcc, s70, v162
	global_load_dwordx4 v[158:161], v[140:141], off
	s_nop 0
	v_addc_co_u32_e32 v163, vcc, 0, v163, vcc
	global_load_dwordx4 v[204:207], v[162:163], off
	v_mfma_f32_32x32x16_bf16 v[82:97], v[208:211], v[118:121], v[82:97]
	v_mfma_f32_32x32x16_bf16 v[82:97], v[216:219], v[114:117], v[82:97]
	v_mfma_f32_32x32x16_bf16 v[82:97], v[226:229], v[110:113], v[82:97]
	v_mfma_f32_32x32x16_bf16 v[82:97], v[234:237], v[106:109], v[82:97]
	v_mfma_f32_32x32x16_bf16 v[82:97], v[242:245], v[102:105], v[82:97]
	s_waitcnt lgkmcnt(0)
; #define SBAR() __builtin_amdgcn_sched_barrier(0)
; template <int OFF> __device__ __forceinline__ s16x4 tr_read(int vb) { s16x4 r; asm volatile("ds_read_b64_tr_b16 %0, %1 offset:%2" : "=&v"(r) : "v"(vb), "i"(OFF) : "memory"); return r; }
; template <int D0> __device__ __forceinline__ void pv_one(f32x16& od, int vb, bf16x8 pa0, bf16x8 pa1, bf16x8 pa2, bf16x8 pa3) {
;   const s16x4 l0 = tr_read<v_rd_off(D0, 0, 0)>(vb), h0 = tr_read<v_rd_off(D0, 0, 1)>(vb), l1 = tr_read<v_rd_off(D0, 1, 0)>(vb), h1 = tr_read<v_rd_off(D0, 1, 1)>(vb);
;   const s16x4 l2 = tr_read<v_rd_off(D0, 2, 0)>(vb), h2 = tr_read<v_rd_off(D0, 2, 1)>(vb), l3 = tr_read<v_rd_off(D0, 3, 0)>(vb), h3 = tr_read<v_rd_off(D0, 3, 1)>(vb);
;   asm volatile("s_waitcnt lgkmcnt(0)" ::: "memory"); SBAR();
;     ...
;   od = __builtin_amdgcn_mfma_f32_32x32x16_bf16(pa0, PK(l0, h0), od, 0, 0, 0);
;   od = __builtin_amdgcn_mfma_f32_32x32x16_bf16(pa1, PK(l1, h1), od, 0, 0, 0);
;   od = __builtin_amdgcn_mfma_f32_32x32x16_bf16(pa2, PK(l2, h2), od, 0, 0, 0);
;   od = __builtin_amdgcn_mfma_f32_32x32x16_bf16(pa3, PK(l3, h3), od, 0, 0, 0);
;     ...
; }
; __device__ __forceinline__ void pv_d0(f32x16* o, int vb, bf16x8 pa0, bf16x8 pa1, bf16x8 pa2, bf16x8 pa3) {
;   pv_one<0>(o[0], vb, pa0, pa1, pa2, pa3); pv_one<1>(o[1], vb, pa0, pa1, pa2, pa3); pv_one<2>(o[2], vb, pa0, pa1, pa2, pa3); pv_one<3>(o[3], vb, pa0, pa1, pa2, pa3);
; }
; template <int DQK>
; __device__ __forceinline__ void partialSM(f32x16& p0, f32x16& p1, float& m_reg, float& mn, float& alpha) {
;     ...
;   float pmax = p0[0];
; #pragma unroll
;   for (int r = 1; r < 16; ++r) pmax = fmaxf(pmax, p0[r]);
; #pragma unroll
;   for (int r = 0; r < 16; ++r) pmax = fmaxf(pmax, p1[r]);
;   { auto rr = __builtin_amdgcn_permlane32_swap(__float_as_uint(pmax), __float_as_uint(pmax), false, false);
;     pmax = fmaxf(__uint_as_float(rr[0]), __uint_as_float(rr[1])); }
;   if (__builtin_expect(__all(pmax - m_reg <= THR / SCALE), 1)) { mn = m_reg; alpha = 1.f; }
;   else { mn = fmaxf(m_reg, pmax); alpha = __builtin_amdgcn_exp2f((m_reg - mn) * C); m_reg = mn; }
	v_mfma_f32_32x32x16_bf16 v[82:97], v[250:253], v[98:101], v[82:97]
	ds_read_b64_tr_b16 v[208:209], v169 offset:0
	ds_read_b64_tr_b16 v[210:211], v169 offset:0x800
	ds_read_b64_tr_b16 v[212:213], v169 offset:0x1000
	ds_read_b64_tr_b16 v[214:215], v169 offset:0x1800
	ds_read_b64_tr_b16 v[216:217], v169 offset:0x2000
	ds_read_b64_tr_b16 v[218:219], v169 offset:0x2800
	ds_read_b64_tr_b16 v[220:221], v169 offset:0x3000
	ds_read_b64_tr_b16 v[222:223], v169 offset:0x3800
	s_waitcnt lgkmcnt(0)
	s_nop 0
	v_mfma_f32_32x32x16_bf16 v[2:17], v[142:145], v[208:211], v[2:17]
	ds_read_b64_tr_b16 v[208:209], v169 offset:0x200
	ds_read_b64_tr_b16 v[210:211], v169 offset:0xa00
	v_mfma_f32_32x32x16_bf16 v[2:17], v[132:135], v[212:215], v[2:17]
	ds_read_b64_tr_b16 v[212:213], v169 offset:0x1200
	ds_read_b64_tr_b16 v[214:215], v169 offset:0x1a00
	v_mfma_f32_32x32x16_bf16 v[2:17], v[136:139], v[216:219], v[2:17]
	ds_read_b64_tr_b16 v[216:217], v169 offset:0x2200
	ds_read_b64_tr_b16 v[218:219], v169 offset:0x2a00
	ds_read_b64_tr_b16 v[226:227], v169 offset:0x3200
	ds_read_b64_tr_b16 v[228:229], v169 offset:0x3a00
	v_mfma_f32_32x32x16_bf16 v[2:17], v[196:199], v[220:223], v[2:17]
	s_waitcnt lgkmcnt(6)
	v_mfma_f32_32x32x16_bf16 v[50:65], v[142:145], v[208:211], v[50:65]
	ds_read_b64_tr_b16 v[208:209], v169 offset:0x400
	ds_read_b64_tr_b16 v[210:211], v169 offset:0xc00
	s_waitcnt lgkmcnt(6)
	v_mfma_f32_32x32x16_bf16 v[50:65], v[132:135], v[212:215], v[50:65]
	ds_read_b64_tr_b16 v[212:213], v169 offset:0x1400
	ds_read_b64_tr_b16 v[214:215], v169 offset:0x1c00
	s_waitcnt lgkmcnt(6)
	v_mfma_f32_32x32x16_bf16 v[50:65], v[136:139], v[216:219], v[50:65]
	ds_read_b64_tr_b16 v[216:217], v169 offset:0x2400
	ds_read_b64_tr_b16 v[218:219], v169 offset:0x2c00
	ds_read_b64_tr_b16 v[220:221], v169 offset:0x3400
	ds_read_b64_tr_b16 v[222:223], v169 offset:0x3c00
	s_waitcnt lgkmcnt(8)
	v_mfma_f32_32x32x16_bf16 v[50:65], v[196:199], v[226:229], v[50:65]
	s_waitcnt lgkmcnt(6)
	v_mfma_f32_32x32x16_bf16 v[34:49], v[142:145], v[208:211], v[34:49]
	ds_read_b64_tr_b16 v[208:209], v169 offset:0x600
	ds_read_b64_tr_b16 v[210:211], v169 offset:0xe00
	s_waitcnt lgkmcnt(6)
	v_mfma_f32_32x32x16_bf16 v[34:49], v[132:135], v[212:215], v[34:49]
	ds_read_b64_tr_b16 v[212:213], v169 offset:0x1600
	ds_read_b64_tr_b16 v[214:215], v169 offset:0x1e00
	s_waitcnt lgkmcnt(6)
	v_mfma_f32_32x32x16_bf16 v[34:49], v[136:139], v[216:219], v[34:49]
	ds_read_b64_tr_b16 v[216:217], v169 offset:0x2600
	ds_read_b64_tr_b16 v[218:219], v169 offset:0x2e00
	ds_read_b64_tr_b16 v[226:227], v169 offset:0x3600
	ds_read_b64_tr_b16 v[228:229], v169 offset:0x3e00
	s_waitcnt lgkmcnt(8)
	v_mfma_f32_32x32x16_bf16 v[34:49], v[196:199], v[220:223], v[34:49]
	v_max_f32_e32 v131, v67, v67
	v_max_f32_e32 v140, v66, v66
	s_waitcnt lgkmcnt(6)
	v_mfma_f32_32x32x16_bf16 v[18:33], v[142:145], v[208:211], v[18:33]
	v_max_f32_e32 v131, v140, v131
	v_max3_f32 v131, v131, v68, v69
	v_max3_f32 v131, v131, v70, v71
	v_max3_f32 v131, v131, v72, v73
	v_max3_f32 v131, v131, v74, v75
	v_max3_f32 v131, v131, v76, v77
	v_max3_f32 v131, v131, v78, v79
	v_max3_f32 v131, v131, v80, v81
	s_waitcnt lgkmcnt(4)
	v_mfma_f32_32x32x16_bf16 v[18:33], v[132:135], v[212:215], v[18:33]
	v_max3_f32 v131, v131, v82, v83
	v_max3_f32 v131, v131, v84, v85
	v_max3_f32 v131, v131, v86, v87
	v_max3_f32 v131, v131, v88, v89
	v_max3_f32 v131, v131, v90, v91
	v_max3_f32 v131, v131, v92, v93
	v_max3_f32 v131, v131, v94, v95
	v_max3_f32 v131, v131, v96, v97
	s_waitcnt lgkmcnt(2)
	v_mfma_f32_32x32x16_bf16 v[18:33], v[136:139], v[216:219], v[18:33]
	v_mov_b32_e32 v132, v131
	s_nop 1
	v_permlane32_swap_b32_e32 v131, v132
	v_max_f32_e32 v132, v132, v132
	v_max_f32_e32 v131, v131, v131
	v_max_f32_e32 v131, v131, v132
	v_sub_f32_e32 v132, v131, v130
	v_cmp_ge_f32_e32 vcc, s60, v132
	v_max_f32_e32 v132, v130, v130
	v_max_f32_e32 v131, v132, v131
	s_waitcnt lgkmcnt(0)
	v_mfma_f32_32x32x16_bf16 v[18:33], v[196:199], v[226:229], v[18:33]
	v_sub_f32_e32 v132, v130, v131
	v_mul_f32_e32 v132, 0x3e0293ee, v132
	v_exp_f32_e32 v132, v132
	s_cmp_eq_u64 vcc, exec
	s_barrier
	s_waitcnt vmcnt(0)
	s_cselect_b64 s[6:7], -1, 0
	s_waitcnt vmcnt(3)
	ds_write_b128 v173, v[192:195] offset:16384
	s_waitcnt vmcnt(2)
	ds_write_b128 v174, v[200:203] offset:16384
	s_waitcnt vmcnt(1)
	ds_write_b128 v175, v[158:161] offset:49152
	s_waitcnt vmcnt(0)
	ds_write_b128 v176, v[204:207] offset:49152
	v_cndmask_b32_e64 v158, v132, 1.0, s[6:7]
	v_cmp_gt_f32_e32 vcc, 1.0, v158
	s_cbranch_vccz .LBB0_1928
	s_and_saveexec_b64 s[54:55], s[4:5]
	ds_write_b32 v168, v158 offset:128
	s_or_b64 exec, exec, s[54:55]
	s_waitcnt lgkmcnt(0)
	v_add_u32_e32 v144, v151, v146
	ds_read_b128 v[132:135], v144 offset:224
	ds_read_b128 v[136:139], v144 offset:192
	ds_read_b128 v[140:143], v144 offset:160
	ds_read_b128 v[160:163], v144 offset:128
	s_waitcnt lgkmcnt(3)
	v_pk_mul_f32 v[14:15], v[14:15], v[132:133]
	s_waitcnt lgkmcnt(2)
	v_pk_mul_f32 v[10:11], v[10:11], v[136:137]
	s_waitcnt lgkmcnt(1)
	v_pk_mul_f32 v[6:7], v[6:7], v[140:141]
	v_pk_mul_f32 v[16:17], v[16:17], v[134:135]
	v_pk_mul_f32 v[12:13], v[12:13], v[138:139]
	v_pk_mul_f32 v[8:9], v[8:9], v[142:143]
	s_waitcnt lgkmcnt(0)
	v_pk_mul_f32 v[4:5], v[4:5], v[162:163]
	v_pk_mul_f32 v[2:3], v[2:3], v[160:161]
	v_pk_mul_f32 v[62:63], v[62:63], v[132:133]
	v_pk_mul_f32 v[58:59], v[58:59], v[136:137]
	v_pk_mul_f32 v[54:55], v[54:55], v[140:141]
	v_pk_mul_f32 v[64:65], v[64:65], v[134:135]
	v_pk_mul_f32 v[60:61], v[60:61], v[138:139]
	v_pk_mul_f32 v[56:57], v[56:57], v[142:143]
	v_pk_mul_f32 v[52:53], v[52:53], v[162:163]
	v_pk_mul_f32 v[50:51], v[50:51], v[160:161]
	v_pk_mul_f32 v[46:47], v[46:47], v[132:133]
	v_pk_mul_f32 v[42:43], v[42:43], v[136:137]
	v_pk_mul_f32 v[38:39], v[38:39], v[140:141]
	v_pk_mul_f32 v[48:49], v[48:49], v[134:135]
	v_pk_mul_f32 v[44:45], v[44:45], v[138:139]
	v_pk_mul_f32 v[40:41], v[40:41], v[142:143]
	v_pk_mul_f32 v[36:37], v[36:37], v[162:163]
	v_pk_mul_f32 v[34:35], v[34:35], v[160:161]
	v_pk_mul_f32 v[30:31], v[30:31], v[132:133]
	v_pk_mul_f32 v[26:27], v[26:27], v[136:137]
	v_pk_mul_f32 v[22:23], v[22:23], v[140:141]
	v_pk_mul_f32 v[32:33], v[32:33], v[134:135]
	v_pk_mul_f32 v[28:29], v[28:29], v[138:139]
	v_pk_mul_f32 v[24:25], v[24:25], v[142:143]
	v_pk_mul_f32 v[20:21], v[20:21], v[162:163]
	v_pk_mul_f32 v[18:19], v[18:19], v[160:161]

; __device__ __forceinline__ void finishSM(f32x16& p0, f32x16& p1, float alpha, float& l_reg, bf16x8& pa0, bf16x8& pa1, bf16x8& pa2, bf16x8& pa3) {
; #pragma unroll
;   for (int r = 0; r < 16; ++r) p1[r] = __builtin_amdgcn_exp2f(p1[r]);
;   float ps = 0;
; #pragma unroll
;   for (int r = 0; r < 16; ++r) ps += p0[r];
; #pragma unroll
;   for (int r = 0; r < 16; ++r) ps += p1[r];
;   { auto rr = __builtin_amdgcn_permlane32_swap(__float_as_uint(ps), __float_as_uint(ps), false, false);
;     ps = __uint_as_float(rr[0]) + __uint_as_float(rr[1]); }
;   l_reg = l_reg * alpha + ps;
;   pack_p(p0, p1, pa0, pa1, pa2, pa3);
; }
.LBB0_1930:
	ds_read_b128 v[66:69], v177 offset:49152
	ds_read_b128 v[70:73], v177 offset:57344
	v_exp_f32_e32 v142, v142
	v_exp_f32_e32 v143, v143
	v_exp_f32_e32 v140, v140
	s_waitcnt lgkmcnt(1)
	v_mfma_f32_32x32x16_bf16 v[82:97], v[66:69], v[126:129], 0
	v_exp_f32_e32 v141, v141
	v_exp_f32_e32 v136, v136
	v_exp_f32_e32 v137, v137
	v_exp_f32_e32 v132, v132
	v_exp_f32_e32 v133, v133
	v_exp_f32_e32 v130, v130
	v_exp_f32_e32 v131, v131
	s_waitcnt lgkmcnt(0)
	v_mfma_f32_32x32x16_bf16 v[66:81], v[70:73], v[126:129], 0
	ds_read_b128 v[126:129], v178 offset:49152
	ds_read_b128 v[152:155], v178 offset:57344
	ds_read_b128 v[174:177], v179 offset:49152
	ds_read_b128 v[188:191], v179 offset:57344
	v_exp_f32_e32 v144, v144
	v_exp_f32_e32 v145, v145
	v_exp_f32_e32 v134, v134
	v_exp_f32_e32 v135, v135
	s_waitcnt lgkmcnt(3)
	v_mfma_f32_32x32x16_bf16 v[82:97], v[126:129], v[122:125], v[82:97]
	ds_read_b128 v[126:129], v180 offset:49152
	ds_read_b128 v[204:207], v180 offset:57344
	ds_read_b128 v[208:211], v181 offset:49152
	ds_read_b128 v[178:181], v181 offset:57344
	ds_read_b128 v[212:215], v182 offset:49152
	ds_read_b128 v[216:219], v182 offset:57344
	ds_read_b128 v[220:223], v183 offset:49152
	ds_read_b128 v[226:229], v183 offset:57344
	s_waitcnt lgkmcnt(10)
	v_mfma_f32_32x32x16_bf16 v[66:81], v[152:155], v[122:125], v[66:81]
	ds_read_b128 v[122:125], v184 offset:49152
	ds_read_b128 v[152:155], v184 offset:57344
	s_waitcnt lgkmcnt(11)
	v_mfma_f32_32x32x16_bf16 v[82:97], v[174:177], v[118:121], v[82:97]
	s_waitcnt lgkmcnt(10)
	v_mfma_f32_32x32x16_bf16 v[66:81], v[188:191], v[118:121], v[66:81]
	v_add_f32_e32 v118, 0, v195
	v_add_f32_e32 v118, v196, v118
	v_add_f32_e32 v118, v197, v118
	v_add_f32_e32 v118, v198, v118
	v_add_f32_e32 v118, v199, v118
	v_add_f32_e32 v118, v201, v118
	v_add_f32_e32 v118, v200, v118
	s_waitcnt lgkmcnt(9)
	v_mfma_f32_32x32x16_bf16 v[82:97], v[126:129], v[114:117], v[82:97]
	v_add_f32_e32 v118, v202, v118
	v_add_f32_e32 v118, v159, v118
	v_add_f32_e32 v118, v160, v118
	v_exp_f32_e32 v120, v138
	v_exp_f32_e32 v121, v139
	v_cvt_pk_bf16_f32 v119, v132, v133
	s_waitcnt lgkmcnt(8)
	v_mfma_f32_32x32x16_bf16 v[66:81], v[204:207], v[114:117], v[66:81]
	v_add_f32_e32 v114, v161, v118
	v_add_f32_e32 v114, v163, v114
	v_add_f32_e32 v114, v162, v114
	v_add_f32_e32 v114, v192, v114
	v_add_f32_e32 v114, v193, v114
	v_add_f32_e32 v114, v194, v114
	v_add_f32_e32 v114, v142, v114
	s_waitcnt lgkmcnt(7)
	v_mfma_f32_32x32x16_bf16 v[82:97], v[208:211], v[110:113], v[82:97]
	v_add_f32_e32 v114, v143, v114
	v_add_f32_e32 v114, v140, v114
	v_add_f32_e32 v114, v141, v114
	v_add_f32_e32 v114, v136, v114
	v_add_f32_e32 v114, v137, v114
	v_add_f32_e32 v114, v132, v114
	v_add_f32_e32 v114, v133, v114
	s_waitcnt lgkmcnt(6)
	v_mfma_f32_32x32x16_bf16 v[66:81], v[178:181], v[110:113], v[66:81]
	v_add_f32_e32 v110, v130, v114
	v_add_f32_e32 v110, v131, v110
	v_add_f32_e32 v110, v144, v110
	v_add_f32_e32 v110, v145, v110
	v_add_f32_e32 v110, v120, v110
	v_add_f32_e32 v110, v121, v110
	v_add_f32_e32 v110, v134, v110
	s_waitcnt lgkmcnt(5)
	v_mfma_f32_32x32x16_bf16 v[82:97], v[212:215], v[106:109], v[82:97]
	v_add_f32_e32 v110, v135, v110
	v_mov_b32_e32 v111, v110
	s_nop 1
	v_permlane32_swap_b32_e32 v110, v111
	v_cvt_pk_bf16_f32 v112, v195, v196
	v_cvt_pk_bf16_f32 v113, v197, v198
	v_cvt_pk_bf16_f32 v114, v199, v201
	s_waitcnt lgkmcnt(4)
	v_mfma_f32_32x32x16_bf16 v[66:81], v[216:219], v[106:109], v[66:81]
	v_cvt_pk_bf16_f32 v115, v200, v202
	v_cvt_pk_bf16_f32 v106, v159, v160
	v_cvt_pk_bf16_f32 v107, v161, v163
	v_cvt_pk_bf16_f32 v108, v162, v192
	v_cvt_pk_bf16_f32 v109, v193, v194
	v_cvt_pk_bf16_f32 v116, v142, v143
	v_cvt_pk_bf16_f32 v117, v140, v141
	s_waitcnt lgkmcnt(3)
	v_mfma_f32_32x32x16_bf16 v[82:97], v[220:223], v[102:105], v[82:97]
	v_cvt_pk_bf16_f32 v118, v136, v137
	v_permlane32_swap_b32_e32 v112, v114
	v_permlane32_swap_b32_e32 v113, v115
	v_permlane32_swap_b32_e32 v106, v108
	s_waitcnt lgkmcnt(2)
	v_mfma_f32_32x32x16_bf16 v[66:81], v[226:229], v[102:105], v[66:81]
	v_cvt_pk_bf16_f32 v102, v130, v131
	v_cvt_pk_bf16_f32 v103, v144, v145
	v_cvt_pk_bf16_f32 v104, v120, v121
	v_cvt_pk_bf16_f32 v105, v134, v135
	v_permlane32_swap_b32_e32 v107, v109
	v_permlane32_swap_b32_e32 v116, v118
	s_waitcnt lgkmcnt(1)
	v_mfma_f32_32x32x16_bf16 v[82:97], v[122:125], v[98:101], v[82:97]
	v_permlane32_swap_b32_e32 v117, v119
	v_permlane32_swap_b32_e32 v102, v104
	v_permlane32_swap_b32_e32 v103, v105
	s_waitcnt lgkmcnt(0)
	v_mfma_f32_32x32x16_bf16 v[66:81], v[152:155], v[98:101], v[66:81]
	ds_read_b64_tr_b16 v[98:99], v172 offset:0
	ds_read_b64_tr_b16 v[100:101], v172 offset:0x800
	ds_read_b64_tr_b16 v[120:121], v172 offset:0x1000
	ds_read_b64_tr_b16 v[122:123], v172 offset:0x1800
	ds_read_b64_tr_b16 v[124:125], v172 offset:0x2000
	ds_read_b64_tr_b16 v[126:127], v172 offset:0x2800
	ds_read_b64_tr_b16 v[128:129], v172 offset:0x3000
	ds_read_b64_tr_b16 v[130:131], v172 offset:0x3800
	s_waitcnt lgkmcnt(0)
	s_nop 0
	v_mfma_f32_32x32x16_bf16 v[2:17], v[112:115], v[98:101], v[2:17]
	ds_read_b64_tr_b16 v[98:99], v172 offset:0x200
	ds_read_b64_tr_b16 v[100:101], v172 offset:0xa00
	v_mfma_f32_32x32x16_bf16 v[2:17], v[106:109], v[120:123], v[2:17]
	ds_read_b64_tr_b16 v[120:121], v172 offset:0x1200
	ds_read_b64_tr_b16 v[122:123], v172 offset:0x1a00
	v_mfma_f32_32x32x16_bf16 v[2:17], v[116:119], v[124:127], v[2:17]
	ds_read_b64_tr_b16 v[124:125], v172 offset:0x2200
	ds_read_b64_tr_b16 v[126:127], v172 offset:0x2a00
	ds_read_b64_tr_b16 v[132:133], v172 offset:0x3200
	ds_read_b64_tr_b16 v[134:135], v172 offset:0x3a00
	v_mfma_f32_32x32x16_bf16 v[2:17], v[102:105], v[128:131], v[2:17]
	s_waitcnt lgkmcnt(6)
; #define SBAR() __builtin_amdgcn_sched_barrier(0)
; template <int OFF> __device__ __forceinline__ s16x4 tr_read(int vb) { s16x4 r; asm volatile("ds_read_b64_tr_b16 %0, %1 offset:%2" : "=&v"(r) : "v"(vb), "i"(OFF) : "memory"); return r; }
; template <int D0> __device__ __forceinline__ void pv_one(f32x16& od, int vb, bf16x8 pa0, bf16x8 pa1, bf16x8 pa2, bf16x8 pa3) {
;   const s16x4 l0 = tr_read<v_rd_off(D0, 0, 0)>(vb), h0 = tr_read<v_rd_off(D0, 0, 1)>(vb), l1 = tr_read<v_rd_off(D0, 1, 0)>(vb), h1 = tr_read<v_rd_off(D0, 1, 1)>(vb);
;   const s16x4 l2 = tr_read<v_rd_off(D0, 2, 0)>(vb), h2 = tr_read<v_rd_off(D0, 2, 1)>(vb), l3 = tr_read<v_rd_off(D0, 3, 0)>(vb), h3 = tr_read<v_rd_off(D0, 3, 1)>(vb);
;   asm volatile("s_waitcnt lgkmcnt(0)" ::: "memory"); SBAR();
;     ...
;   od = __builtin_amdgcn_mfma_f32_32x32x16_bf16(pa0, PK(l0, h0), od, 0, 0, 0);
;   od = __builtin_amdgcn_mfma_f32_32x32x16_bf16(pa1, PK(l1, h1), od, 0, 0, 0);
;   od = __builtin_amdgcn_mfma_f32_32x32x16_bf16(pa2, PK(l2, h2), od, 0, 0, 0);
;   od = __builtin_amdgcn_mfma_f32_32x32x16_bf16(pa3, PK(l3, h3), od, 0, 0, 0);
;     ...
; }
; __device__ __forceinline__ void pv_d0(f32x16* o, int vb, bf16x8 pa0, bf16x8 pa1, bf16x8 pa2, bf16x8 pa3) {
;   pv_one<0>(o[0], vb, pa0, pa1, pa2, pa3); pv_one<1>(o[1], vb, pa0, pa1, pa2, pa3); pv_one<2>(o[2], vb, pa0, pa1, pa2, pa3); pv_one<3>(o[3], vb, pa0, pa1, pa2, pa3);
; }
; template <int DQK>
; __device__ __forceinline__ void partialSM(f32x16& p0, f32x16& p1, float& m_reg, float& mn, float& alpha) {
;     ...
;   float pmax = p0[0];
; #pragma unroll
;   for (int r = 1; r < 16; ++r) pmax = fmaxf(pmax, p0[r]);
; #pragma unroll
;   for (int r = 0; r < 16; ++r) pmax = fmaxf(pmax, p1[r]);
;   { auto rr = __builtin_amdgcn_permlane32_swap(__float_as_uint(pmax), __float_as_uint(pmax), false, false);
;     pmax = fmaxf(__uint_as_float(rr[0]), __uint_as_float(rr[1])); }
;   if (__builtin_expect(__all(pmax - m_reg <= THR / SCALE), 1)) { mn = m_reg; alpha = 1.f; }
;   else { mn = fmaxf(m_reg, pmax); alpha = __builtin_amdgcn_exp2f((m_reg - mn) * C); m_reg = mn; }
	v_mfma_f32_32x32x16_bf16 v[50:65], v[112:115], v[98:101], v[50:65]
	ds_read_b64_tr_b16 v[98:99], v172 offset:0x400
	ds_read_b64_tr_b16 v[100:101], v172 offset:0xc00
	s_waitcnt lgkmcnt(6)
	v_mfma_f32_32x32x16_bf16 v[50:65], v[106:109], v[120:123], v[50:65]
	ds_read_b64_tr_b16 v[120:121], v172 offset:0x1400
	ds_read_b64_tr_b16 v[122:123], v172 offset:0x1c00
	s_waitcnt lgkmcnt(6)
	v_mfma_f32_32x32x16_bf16 v[50:65], v[116:119], v[124:127], v[50:65]
	ds_read_b64_tr_b16 v[124:125], v172 offset:0x2400
	ds_read_b64_tr_b16 v[126:127], v172 offset:0x2c00
	ds_read_b64_tr_b16 v[128:129], v172 offset:0x3400
	ds_read_b64_tr_b16 v[130:131], v172 offset:0x3c00
	s_waitcnt lgkmcnt(8)
	v_mfma_f32_32x32x16_bf16 v[50:65], v[102:105], v[132:135], v[50:65]
	s_waitcnt lgkmcnt(6)
	v_mfma_f32_32x32x16_bf16 v[34:49], v[112:115], v[98:101], v[34:49]
	ds_read_b64_tr_b16 v[98:99], v172 offset:0x600
	ds_read_b64_tr_b16 v[100:101], v172 offset:0xe00
	s_waitcnt lgkmcnt(6)
	v_mfma_f32_32x32x16_bf16 v[34:49], v[106:109], v[120:123], v[34:49]
	ds_read_b64_tr_b16 v[120:121], v172 offset:0x1600
	ds_read_b64_tr_b16 v[122:123], v172 offset:0x1e00
	s_waitcnt lgkmcnt(6)
	v_mfma_f32_32x32x16_bf16 v[34:49], v[116:119], v[124:127], v[34:49]
	ds_read_b64_tr_b16 v[124:125], v172 offset:0x2600
	ds_read_b64_tr_b16 v[126:127], v172 offset:0x2e00
	ds_read_b64_tr_b16 v[132:133], v172 offset:0x3600
	ds_read_b64_tr_b16 v[134:135], v172 offset:0x3e00
	s_waitcnt lgkmcnt(8)
	v_mfma_f32_32x32x16_bf16 v[34:49], v[102:105], v[128:131], v[34:49]
	s_waitcnt lgkmcnt(6)
	v_mfma_f32_32x32x16_bf16 v[18:33], v[112:115], v[98:101], v[18:33]
	v_max_f32_e32 v128, v83, v83
	v_max_f32_e32 v129, v82, v82
	v_max_f32_e32 v128, v129, v128
	v_max3_f32 v128, v128, v84, v85
	v_max3_f32 v128, v128, v86, v87
	v_max3_f32 v98, v128, v88, v89
	v_max3_f32 v98, v98, v90, v91
	v_max3_f32 v98, v98, v92, v93
	s_waitcnt lgkmcnt(4)
	v_mfma_f32_32x32x16_bf16 v[18:33], v[106:109], v[120:123], v[18:33]
	v_max3_f32 v98, v98, v94, v95
	v_max3_f32 v98, v98, v96, v97
	v_max3_f32 v98, v98, v66, v67
	v_max3_f32 v98, v98, v68, v69
	v_max3_f32 v98, v98, v70, v71
	v_max3_f32 v98, v98, v72, v73
	v_max3_f32 v98, v98, v74, v75
	v_max3_f32 v98, v98, v76, v77
	s_waitcnt lgkmcnt(2)
	v_mfma_f32_32x32x16_bf16 v[18:33], v[116:119], v[124:127], v[18:33]
	v_max3_f32 v98, v98, v78, v79
	v_max3_f32 v98, v98, v80, v81
	v_mov_b32_e32 v99, v98
	s_nop 1
	v_permlane32_swap_b32_e32 v98, v99
	v_max_f32_e32 v99, v99, v99
	v_max_f32_e32 v98, v98, v98
	v_max_f32_e32 v98, v98, v99
	v_max_f32_e32 v99, v186, v186
	v_max_f32_e32 v99, v99, v98
	v_sub_f32_e32 v100, v98, v186
	s_waitcnt lgkmcnt(0)
	v_mfma_f32_32x32x16_bf16 v[18:33], v[102:105], v[132:135], v[18:33]
	v_sub_f32_e32 v98, v186, v99
	v_mul_f32_e32 v98, 0x3e0293ee, v98
	v_exp_f32_e32 v98, v98
	v_cmp_ge_f32_e32 vcc, s60, v100
	s_cmp_eq_u64 vcc, exec
	s_cselect_b64 s[6:7], -1, 0
	v_cndmask_b32_e64 v98, v98, 1.0, s[6:7]
	v_cmp_gt_f32_e32 vcc, 1.0, v98
	s_barrier
	s_cbranch_vccz .LBB0_1934
	s_and_saveexec_b64 s[54:55], s[4:5]
	ds_write_b32 v168, v98 offset:128
	s_or_b64 exec, exec, s[54:55]
	s_waitcnt lgkmcnt(0)
	v_add_u32_e32 v108, v151, v146
	ds_read_b128 v[100:103], v108 offset:224
	ds_read_b128 v[104:107], v108 offset:192
	ds_read_b128 v[112:115], v108 offset:160
	ds_read_b128 v[116:119], v108 offset:128
	s_waitcnt lgkmcnt(3)
	v_pk_mul_f32 v[14:15], v[14:15], v[100:101]
	s_waitcnt lgkmcnt(2)
	v_pk_mul_f32 v[10:11], v[10:11], v[104:105]
	s_waitcnt lgkmcnt(1)
	v_pk_mul_f32 v[6:7], v[6:7], v[112:113]
	v_pk_mul_f32 v[16:17], v[16:17], v[102:103]
	v_pk_mul_f32 v[12:13], v[12:13], v[106:107]
	v_pk_mul_f32 v[8:9], v[8:9], v[114:115]
	s_waitcnt lgkmcnt(0)
	v_pk_mul_f32 v[4:5], v[4:5], v[118:119]
	v_pk_mul_f32 v[2:3], v[2:3], v[116:117]
	v_pk_mul_f32 v[62:63], v[62:63], v[100:101]
	v_pk_mul_f32 v[58:59], v[58:59], v[104:105]
	v_pk_mul_f32 v[54:55], v[54:55], v[112:113]
	v_pk_mul_f32 v[64:65], v[64:65], v[102:103]
	v_pk_mul_f32 v[60:61], v[60:61], v[106:107]
	v_pk_mul_f32 v[56:57], v[56:57], v[114:115]
	v_pk_mul_f32 v[52:53], v[52:53], v[118:119]
	v_pk_mul_f32 v[50:51], v[50:51], v[116:117]
	v_pk_mul_f32 v[46:47], v[46:47], v[100:101]
	v_pk_mul_f32 v[42:43], v[42:43], v[104:105]
	v_pk_mul_f32 v[38:39], v[38:39], v[112:113]
	v_pk_mul_f32 v[48:49], v[48:49], v[102:103]
	v_pk_mul_f32 v[44:45], v[44:45], v[106:107]
	v_pk_mul_f32 v[40:41], v[40:41], v[114:115]
	v_pk_mul_f32 v[36:37], v[36:37], v[118:119]
	v_pk_mul_f32 v[34:35], v[34:35], v[116:117]
	v_pk_mul_f32 v[30:31], v[30:31], v[100:101]
	v_pk_mul_f32 v[26:27], v[26:27], v[104:105]
	v_pk_mul_f32 v[22:23], v[22:23], v[112:113]
	v_pk_mul_f32 v[32:33], v[32:33], v[102:103]
	v_pk_mul_f32 v[28:29], v[28:29], v[106:107]
	v_pk_mul_f32 v[24:25], v[24:25], v[114:115]
	v_pk_mul_f32 v[20:21], v[20:21], v[118:119]
	v_pk_mul_f32 v[18:19], v[18:19], v[116:117]
; #define SBAR() __builtin_amdgcn_sched_barrier(0)
; template <int D0> __device__ __forceinline__ void pv_one(f32x16& od, int vb, bf16x8 pa0, bf16x8 pa1, bf16x8 pa2, bf16x8 pa3) {
;   const s16x4 l0 = tr_read<v_rd_off(D0, 0, 0)>(vb), h0 = tr_read<v_rd_off(D0, 0, 1)>(vb), l1 = tr_read<v_rd_off(D0, 1, 0)>(vb), h1 = tr_read<v_rd_off(D0, 1, 1)>(vb);
;   const s16x4 l2 = tr_read<v_rd_off(D0, 2, 0)>(vb), h2 = tr_read<v_rd_off(D0, 2, 1)>(vb), l3 = tr_read<v_rd_off(D0, 3, 0)>(vb), h3 = tr_read<v_rd_off(D0, 3, 1)>(vb);
;   asm volatile("s_waitcnt lgkmcnt(0)" ::: "memory"); SBAR();
;     ...
;   od = __builtin_amdgcn_mfma_f32_32x32x16_bf16(pa0, PK(l0, h0), od, 0, 0, 0);
;   od = __builtin_amdgcn_mfma_f32_32x32x16_bf16(pa1, PK(l1, h1), od, 0, 0, 0);
;   od = __builtin_amdgcn_mfma_f32_32x32x16_bf16(pa2, PK(l2, h2), od, 0, 0, 0);
;   od = __builtin_amdgcn_mfma_f32_32x32x16_bf16(pa3, PK(l3, h3), od, 0, 0, 0);
;     ...
; }
; __device__ __forceinline__ void pv_d0(f32x16* o, int vb, bf16x8 pa0, bf16x8 pa1, bf16x8 pa2, bf16x8 pa3) {
;   pv_one<0>(o[0], vb, pa0, pa1, pa2, pa3); pv_one<1>(o[1], vb, pa0, pa1, pa2, pa3); pv_one<2>(o[2], vb, pa0, pa1, pa2, pa3); pv_one<3>(o[3], vb, pa0, pa1, pa2, pa3);
; }
; template <int DQK>
; __device__ __forceinline__ void partialSM(f32x16& p0, f32x16& p1, float& m_reg, float& mn, float& alpha) {
;     ...
;   const float mnC = -mn * C;
; #pragma unroll
;   for (int r = 0; r < 16; ++r) p0[r] = fmaf(p0[r], C, mnC);
; #pragma unroll
;   for (int r = 0; r < 16; ++r) p1[r] = fmaf(p1[r], C, mnC);
; #pragma unroll
;   for (int r = 0; r < 16; ++r) p0[r] = __builtin_amdgcn_exp2f(p0[r]);
; }
; __device__ __forceinline__ void finishSM(f32x16& p0, f32x16& p1, float alpha, float& l_reg, bf16x8& pa0, bf16x8& pa1, bf16x8& pa2, bf16x8& pa3) {
; #pragma unroll
;   for (int r = 0; r < 16; ++r) p1[r] = __builtin_amdgcn_exp2f(p1[r]);
;   float ps = 0;
; #pragma unroll
;   for (int r = 0; r < 16; ++r) ps += p0[r];
; #pragma unroll
;   for (int r = 0; r < 16; ++r) ps += p1[r];
;   { auto rr = __builtin_amdgcn_permlane32_swap(__float_as_uint(ps), __float_as_uint(ps), false, false);
;     ps = __uint_as_float(rr[0]) + __uint_as_float(rr[1]); }
;   l_reg = l_reg * alpha + ps;
;   pack_p(p0, p1, pa0, pa1, pa2, pa3);
; }
.LBB0_1934:
	v_cndmask_b32_e64 v99, v99, v186, s[6:7]
	v_mul_f32_e32 v99, 0xbe0293ee, v99
	v_fmamk_f32 v82, v82, 0x3e0293ee, v99
	v_fmamk_f32 v83, v83, 0x3e0293ee, v99
	v_fmamk_f32 v108, v95, 0x3e0293ee, v99
	v_fmamk_f32 v95, v76, 0x3e0293ee, v99
	v_exp_f32_e32 v76, v82
	v_fmamk_f32 v84, v84, 0x3e0293ee, v99
	v_fmamk_f32 v109, v96, 0x3e0293ee, v99
	v_fmamk_f32 v96, v77, 0x3e0293ee, v99
	v_exp_f32_e32 v77, v83
	v_fmamk_f32 v85, v85, 0x3e0293ee, v99
	v_fmamk_f32 v112, v97, 0x3e0293ee, v99
	v_fmamk_f32 v97, v78, 0x3e0293ee, v99
	v_exp_f32_e32 v78, v84
	v_fmamk_f32 v86, v86, 0x3e0293ee, v99
	v_fmamk_f32 v66, v66, 0x3e0293ee, v99
	v_exp_f32_e32 v82, v85
	v_fmamk_f32 v100, v87, 0x3e0293ee, v99
	v_fmamk_f32 v101, v88, 0x3e0293ee, v99
	v_fmamk_f32 v102, v89, 0x3e0293ee, v99
	v_fmamk_f32 v103, v90, 0x3e0293ee, v99
	v_fmamk_f32 v104, v91, 0x3e0293ee, v99
	v_fmamk_f32 v105, v92, 0x3e0293ee, v99
	v_fmamk_f32 v106, v93, 0x3e0293ee, v99
	v_fmamk_f32 v107, v94, 0x3e0293ee, v99
	v_fmamk_f32 v67, v67, 0x3e0293ee, v99
	v_fmamk_f32 v87, v68, 0x3e0293ee, v99
	v_fmamk_f32 v88, v69, 0x3e0293ee, v99
	v_fmamk_f32 v89, v70, 0x3e0293ee, v99
	v_fmamk_f32 v90, v71, 0x3e0293ee, v99
	v_fmamk_f32 v91, v72, 0x3e0293ee, v99
	v_fmamk_f32 v92, v73, 0x3e0293ee, v99
	v_fmamk_f32 v93, v74, 0x3e0293ee, v99
	v_fmamk_f32 v94, v75, 0x3e0293ee, v99
	v_exp_f32_e32 v83, v86
	v_fmamk_f32 v79, v79, 0x3e0293ee, v99
	v_fmamk_f32 v80, v80, 0x3e0293ee, v99
	v_fmac_f32_e32 v99, 0x3e0293ee, v81
	v_exp_f32_e32 v81, v66
	v_add_f32_e32 v66, 0, v76
	v_exp_f32_e32 v84, v100
	v_add_f32_e32 v66, v77, v66
	v_exp_f32_e32 v85, v101
	v_add_f32_e32 v66, v78, v66
	v_exp_f32_e32 v86, v102
	v_add_f32_e32 v66, v82, v66
	v_exp_f32_e32 v68, v103
	v_add_f32_e32 v66, v83, v66
	v_exp_f32_e32 v69, v104
	v_add_f32_e32 v66, v84, v66
	v_exp_f32_e32 v70, v105
	v_add_f32_e32 v66, v85, v66
	v_exp_f32_e32 v71, v106
	v_add_f32_e32 v66, v86, v66
	v_exp_f32_e32 v72, v107
	v_add_f32_e32 v66, v68, v66
	v_exp_f32_e32 v73, v108
	v_add_f32_e32 v66, v69, v66
	v_exp_f32_e32 v74, v109
	v_add_f32_e32 v66, v70, v66
	v_exp_f32_e32 v75, v112
	v_add_f32_e32 v66, v71, v66
	v_add_f32_e32 v66, v72, v66
	v_exp_f32_e32 v100, v67
	v_add_f32_e32 v66, v73, v66
	v_exp_f32_e32 v87, v87
	v_add_f32_e32 v66, v74, v66
	v_exp_f32_e32 v88, v88
	v_add_f32_e32 v66, v75, v66
	v_exp_f32_e32 v89, v89
	v_add_f32_e32 v66, v81, v66
	v_exp_f32_e32 v90, v90
	v_add_f32_e32 v66, v100, v66
	v_exp_f32_e32 v91, v91
	v_add_f32_e32 v66, v87, v66
	v_exp_f32_e32 v92, v92
	v_add_f32_e32 v66, v88, v66
	v_exp_f32_e32 v93, v93
	v_add_f32_e32 v66, v89, v66
	v_exp_f32_e32 v94, v94
	v_add_f32_e32 v66, v90, v66
	v_exp_f32_e32 v95, v95
	v_add_f32_e32 v66, v91, v66
	v_exp_f32_e32 v96, v96
	v_add_f32_e32 v66, v92, v66
	v_exp_f32_e32 v97, v97
	v_add_f32_e32 v66, v93, v66
	v_exp_f32_e32 v101, v79
	v_add_f32_e32 v66, v94, v66
	v_exp_f32_e32 v102, v80
	v_add_f32_e32 v66, v95, v66
	v_exp_f32_e32 v99, v99
	v_add_f32_e32 v66, v96, v66
	v_add_f32_e32 v66, v97, v66
	v_add_f32_e32 v66, v101, v66
	v_add_f32_e32 v66, v102, v66
	v_add_f32_e32 v66, v99, v66
	v_mov_b32_e32 v67, v66
	s_nop 1
	v_permlane32_swap_b32_e32 v66, v67
	v_cvt_pk_bf16_f32 v76, v76, v77
	v_cvt_pk_bf16_f32 v77, v78, v82
	v_cvt_pk_bf16_f32 v78, v83, v84
	v_cvt_pk_bf16_f32 v79, v85, v86
	v_cvt_pk_bf16_f32 v68, v68, v69
	v_cvt_pk_bf16_f32 v69, v70, v71
	v_cvt_pk_bf16_f32 v70, v72, v73
	v_cvt_pk_bf16_f32 v71, v74, v75
	v_cvt_pk_bf16_f32 v72, v81, v100
	v_cvt_pk_bf16_f32 v73, v87, v88
	v_cvt_pk_bf16_f32 v74, v89, v90
	v_cvt_pk_bf16_f32 v75, v91, v92
	v_cvt_pk_bf16_f32 v80, v93, v94
	v_cvt_pk_bf16_f32 v81, v95, v96
	v_cvt_pk_bf16_f32 v82, v97, v101
	v_cvt_pk_bf16_f32 v83, v102, v99
	v_permlane32_swap_b32_e32 v76, v78
	v_permlane32_swap_b32_e32 v77, v79
	v_permlane32_swap_b32_e32 v68, v70
	v_permlane32_swap_b32_e32 v69, v71
	v_permlane32_swap_b32_e32 v72, v74
	v_permlane32_swap_b32_e32 v73, v75
	v_permlane32_swap_b32_e32 v80, v82
	v_permlane32_swap_b32_e32 v81, v83
	ds_read_b64_tr_b16 v[84:85], v169 offset:0
	ds_read_b64_tr_b16 v[86:87], v169 offset:0x800
	ds_read_b64_tr_b16 v[88:89], v169 offset:0x1000
	ds_read_b64_tr_b16 v[90:91], v169 offset:0x1800
	ds_read_b64_tr_b16 v[92:93], v169 offset:0x2000
	ds_read_b64_tr_b16 v[94:95], v169 offset:0x2800
	ds_read_b64_tr_b16 v[100:101], v169 offset:0x3000
	ds_read_b64_tr_b16 v[102:103], v169 offset:0x3800
	s_waitcnt lgkmcnt(0)
	s_nop 0
	v_mfma_f32_32x32x16_bf16 v[2:17], v[76:79], v[84:87], v[2:17]
	ds_read_b64_tr_b16 v[84:85], v169 offset:0x200
	ds_read_b64_tr_b16 v[86:87], v169 offset:0xa00
	v_mfma_f32_32x32x16_bf16 v[2:17], v[68:71], v[88:91], v[2:17]
	ds_read_b64_tr_b16 v[88:89], v169 offset:0x1200
	ds_read_b64_tr_b16 v[90:91], v169 offset:0x1a00
	v_mfma_f32_32x32x16_bf16 v[2:17], v[72:75], v[92:95], v[2:17]
	ds_read_b64_tr_b16 v[92:93], v169 offset:0x2200
	ds_read_b64_tr_b16 v[94:95], v169 offset:0x2a00
	ds_read_b64_tr_b16 v[104:105], v169 offset:0x3200
	ds_read_b64_tr_b16 v[106:107], v169 offset:0x3a00
	v_mfma_f32_32x32x16_bf16 v[2:17], v[80:83], v[100:103], v[2:17]
	s_waitcnt lgkmcnt(6)
	v_mfma_f32_32x32x16_bf16 v[50:65], v[76:79], v[84:87], v[50:65]
	ds_read_b64_tr_b16 v[84:85], v169 offset:0x400
	ds_read_b64_tr_b16 v[86:87], v169 offset:0xc00
	s_waitcnt lgkmcnt(6)
	v_mfma_f32_32x32x16_bf16 v[50:65], v[68:71], v[88:91], v[50:65]
	ds_read_b64_tr_b16 v[88:89], v169 offset:0x1400
	ds_read_b64_tr_b16 v[90:91], v169 offset:0x1c00
	s_waitcnt lgkmcnt(6)
	v_mfma_f32_32x32x16_bf16 v[50:65], v[72:75], v[92:95], v[50:65]
	ds_read_b64_tr_b16 v[92:93], v169 offset:0x2400
	ds_read_b64_tr_b16 v[94:95], v169 offset:0x2c00
	ds_read_b64_tr_b16 v[100:101], v169 offset:0x3400
	ds_read_b64_tr_b16 v[102:103], v169 offset:0x3c00
	s_waitcnt lgkmcnt(8)
	v_mfma_f32_32x32x16_bf16 v[50:65], v[80:83], v[104:107], v[50:65]
	s_waitcnt lgkmcnt(6)
	v_mfma_f32_32x32x16_bf16 v[34:49], v[76:79], v[84:87], v[34:49]
	ds_read_b64_tr_b16 v[84:85], v169 offset:0x600
	ds_read_b64_tr_b16 v[86:87], v169 offset:0xe00
	s_waitcnt lgkmcnt(6)
	v_mfma_f32_32x32x16_bf16 v[34:49], v[68:71], v[88:91], v[34:49]
	ds_read_b64_tr_b16 v[88:89], v169 offset:0x1600
	ds_read_b64_tr_b16 v[90:91], v169 offset:0x1e00
	s_waitcnt lgkmcnt(6)
	v_mfma_f32_32x32x16_bf16 v[34:49], v[72:75], v[92:95], v[34:49]
	ds_read_b64_tr_b16 v[92:93], v169 offset:0x2600
	ds_read_b64_tr_b16 v[94:95], v169 offset:0x2e00
	ds_read_b64_tr_b16 v[104:105], v169 offset:0x3600
	ds_read_b64_tr_b16 v[106:107], v169 offset:0x3e00
	s_waitcnt lgkmcnt(8)
	v_mfma_f32_32x32x16_bf16 v[34:49], v[80:83], v[100:103], v[34:49]
	s_waitcnt lgkmcnt(6)
	v_mfma_f32_32x32x16_bf16 v[18:33], v[76:79], v[84:87], v[18:33]
	s_waitcnt lgkmcnt(4)
	v_mfma_f32_32x32x16_bf16 v[18:33], v[68:71], v[88:91], v[18:33]
	s_waitcnt lgkmcnt(2)
	v_mfma_f32_32x32x16_bf16 v[18:33], v[72:75], v[92:95], v[18:33]
	s_waitcnt lgkmcnt(0)
	v_mfma_f32_32x32x16_bf16 v[18:33], v[80:83], v[104:107], v[18:33]
	s_and_saveexec_b64 s[6:7], s[4:5]
	s_cbranch_execz .LBB0_1918
; __device__ __forceinline__ void finishSM(f32x16& p0, f32x16& p1, float alpha, float& l_reg, bf16x8& pa0, bf16x8& pa1, bf16x8& pa2, bf16x8& pa3) {
;     ...
;   { auto rr = __builtin_amdgcn_permlane32_swap(__float_as_uint(ps), __float_as_uint(ps), false, false);
;     ps = __uint_as_float(rr[0]) + __uint_as_float(rr[1]); }
;   l_reg = l_reg * alpha + ps;
; template <int DQK, int MODE, int SDEPTH, int ldq, int ldk, int ldv, int ldo, int ldg> ...
;     ...
;     if (hi == 0) li_l[r32] = l_reg; asm volatile("s_waitcnt lgkmcnt(0)" ::: "memory");
	v_add_f32_e32 v68, v110, v111
	v_fmac_f32_e32 v68, v171, v158
	v_add_f32_e32 v66, v66, v67
	v_fmac_f32_e32 v66, v68, v98
	ds_write_b32 v168, v66
	s_branch .LBB0_1918

; #define SBAR() __builtin_amdgcn_sched_barrier(0)
; template <int OFF> __device__ __forceinline__ s16x4 tr_read(int vb) { s16x4 r; asm volatile("ds_read_b64_tr_b16 %0, %1 offset:%2" : "=&v"(r) : "v"(vb), "i"(OFF) : "memory"); return r; }
; template <int D0> __device__ __forceinline__ void pv_one(f32x16& od, int vb, bf16x8 pa0, bf16x8 pa1, bf16x8 pa2, bf16x8 pa3) {
;   const s16x4 l0 = tr_read<v_rd_off(D0, 0, 0)>(vb), h0 = tr_read<v_rd_off(D0, 0, 1)>(vb), l1 = tr_read<v_rd_off(D0, 1, 0)>(vb), h1 = tr_read<v_rd_off(D0, 1, 1)>(vb);
;   const s16x4 l2 = tr_read<v_rd_off(D0, 2, 0)>(vb), h2 = tr_read<v_rd_off(D0, 2, 1)>(vb), l3 = tr_read<v_rd_off(D0, 3, 0)>(vb), h3 = tr_read<v_rd_off(D0, 3, 1)>(vb);
;   asm volatile("s_waitcnt lgkmcnt(0)" ::: "memory"); SBAR();
;     ...
;   od = __builtin_amdgcn_mfma_f32_32x32x16_bf16(pa0, PK(l0, h0), od, 0, 0, 0);
;   od = __builtin_amdgcn_mfma_f32_32x32x16_bf16(pa1, PK(l1, h1), od, 0, 0, 0);
;   od = __builtin_amdgcn_mfma_f32_32x32x16_bf16(pa2, PK(l2, h2), od, 0, 0, 0);
;   od = __builtin_amdgcn_mfma_f32_32x32x16_bf16(pa3, PK(l3, h3), od, 0, 0, 0);
;     ...
; }
; __device__ __forceinline__ void pv_d0(f32x16* o, int vb, bf16x8 pa0, bf16x8 pa1, bf16x8 pa2, bf16x8 pa3) {
;   pv_one<0>(o[0], vb, pa0, pa1, pa2, pa3); pv_one<1>(o[1], vb, pa0, pa1, pa2, pa3); pv_one<2>(o[2], vb, pa0, pa1, pa2, pa3); pv_one<3>(o[3], vb, pa0, pa1, pa2, pa3);
; }
.LBB0_1968:
	s_lshl_b32 s6, s6, 14
	v_add_u32_e32 v248, s6, v238
	ds_read_b64_tr_b16 v[82:83], v248 offset:0
	ds_read_b64_tr_b16 v[84:85], v248 offset:0x800
	ds_read_b64_tr_b16 v[86:87], v248 offset:0x1000
	ds_read_b64_tr_b16 v[88:89], v248 offset:0x1800
	ds_read_b64_tr_b16 v[90:91], v248 offset:0x2000
	ds_read_b64_tr_b16 v[92:93], v248 offset:0x2800
	ds_read_b64_tr_b16 v[94:95], v248 offset:0x3000
	ds_read_b64_tr_b16 v[96:97], v248 offset:0x3800
	s_waitcnt lgkmcnt(0)
	s_nop 0
	v_mfma_f32_32x32x16_bf16 v[50:65], v[66:69], v[82:85], v[50:65]
	ds_read_b64_tr_b16 v[82:83], v248 offset:0x200
	ds_read_b64_tr_b16 v[84:85], v248 offset:0xa00
	v_mfma_f32_32x32x16_bf16 v[50:65], v[70:73], v[86:89], v[50:65]
	ds_read_b64_tr_b16 v[86:87], v248 offset:0x1200
	ds_read_b64_tr_b16 v[88:89], v248 offset:0x1a00
	v_mfma_f32_32x32x16_bf16 v[50:65], v[74:77], v[90:93], v[50:65]
	ds_read_b64_tr_b16 v[90:91], v248 offset:0x2200
	ds_read_b64_tr_b16 v[92:93], v248 offset:0x2a00
	ds_read_b64_tr_b16 v[222:223], v248 offset:0x3200
	ds_read_b64_tr_b16 v[224:225], v248 offset:0x3a00
	v_mfma_f32_32x32x16_bf16 v[50:65], v[78:81], v[94:97], v[50:65]
	s_waitcnt lgkmcnt(6)
	v_mfma_f32_32x32x16_bf16 v[34:49], v[66:69], v[82:85], v[34:49]
	ds_read_b64_tr_b16 v[82:83], v248 offset:0x400
	ds_read_b64_tr_b16 v[84:85], v248 offset:0xc00
	s_waitcnt lgkmcnt(6)
	v_mfma_f32_32x32x16_bf16 v[34:49], v[70:73], v[86:89], v[34:49]
	ds_read_b64_tr_b16 v[86:87], v248 offset:0x1400
	ds_read_b64_tr_b16 v[88:89], v248 offset:0x1c00
	s_waitcnt lgkmcnt(6)
	v_mfma_f32_32x32x16_bf16 v[34:49], v[74:77], v[90:93], v[34:49]
	ds_read_b64_tr_b16 v[90:91], v248 offset:0x2400
	ds_read_b64_tr_b16 v[92:93], v248 offset:0x2c00
	ds_read_b64_tr_b16 v[94:95], v248 offset:0x3400
	ds_read_b64_tr_b16 v[96:97], v248 offset:0x3c00
	s_waitcnt lgkmcnt(8)
	v_mfma_f32_32x32x16_bf16 v[34:49], v[78:81], v[222:225], v[34:49]
	s_waitcnt lgkmcnt(6)
	v_mfma_f32_32x32x16_bf16 v[18:33], v[66:69], v[82:85], v[18:33]
	ds_read_b64_tr_b16 v[82:83], v248 offset:0x600
	ds_read_b64_tr_b16 v[84:85], v248 offset:0xe00
	s_waitcnt lgkmcnt(6)
	v_mfma_f32_32x32x16_bf16 v[18:33], v[70:73], v[86:89], v[18:33]
	ds_read_b64_tr_b16 v[86:87], v248 offset:0x1600
	ds_read_b64_tr_b16 v[88:89], v248 offset:0x1e00
	s_waitcnt lgkmcnt(6)
	v_mfma_f32_32x32x16_bf16 v[18:33], v[74:77], v[90:93], v[18:33]
	ds_read_b64_tr_b16 v[90:91], v248 offset:0x2600
	ds_read_b64_tr_b16 v[92:93], v248 offset:0x2e00
	ds_read_b64_tr_b16 v[222:223], v248 offset:0x3600
	ds_read_b64_tr_b16 v[224:225], v248 offset:0x3e00
	s_waitcnt lgkmcnt(8)
	v_mfma_f32_32x32x16_bf16 v[18:33], v[78:81], v[94:97], v[18:33]
	s_waitcnt lgkmcnt(6)
	v_mfma_f32_32x32x16_bf16 v[2:17], v[66:69], v[82:85], v[2:17]
	s_andn2_b64 vcc, exec, s[60:61]
	s_waitcnt lgkmcnt(4)
	v_mfma_f32_32x32x16_bf16 v[2:17], v[70:73], v[86:89], v[2:17]
	s_waitcnt lgkmcnt(2)
	v_mfma_f32_32x32x16_bf16 v[2:17], v[74:77], v[90:93], v[2:17]
	s_waitcnt lgkmcnt(0)
	v_mfma_f32_32x32x16_bf16 v[2:17], v[78:81], v[222:225], v[2:17]
	s_cbranch_vccnz .LBB0_1954
	s_xor_b32 s6, s6, 0x4000
	s_waitcnt vmcnt(0)
	s_add_i32 s6, s6, 0
	v_add_u32_e32 v66, s6, v231
	s_waitcnt vmcnt(1)
	ds_write_b128 v66, v[106:109]
	v_add_u32_e32 v66, s6, v232
	s_cmp_gt_u32 s74, 2
	s_waitcnt vmcnt(0)
	ds_write_b128 v66, v[142:145]
	s_cbranch_scc1 .LBB0_1954
	v_add_u32_e32 v67, s6, v236
	v_add_u32_e32 v66, s6, v237
	ds_write_b128 v67, v[102:105] offset:32768
	ds_write_b128 v66, v[134:137] offset:32768
	s_branch .LBB0_1954
